# one static s_setprio 1 for the younger wave half per tile, all per-segment priority flips removed from the three large GEMM loops
# speedup vs baseline: 1.0112x; 1.0112x over previous
.LBB0_328:
	s_ashr_i32 s31, s30, 31
	s_lshl_b64 s[34:35], s[30:31], 19
	s_add_u32 s34, s84, s34
	s_addc_u32 s35, s85, s35
	s_and_b64 s[38:39], s[4:5], exec
	s_cselect_b32 s7, s35, s93
	s_cselect_b32 s11, s34, s92
	s_ashr_i32 s29, s28, 31
	s_lshl_b64 s[38:39], s[28:29], 19
	s_add_u32 s38, s56, s38
	s_addc_u32 s39, s57, s39
	s_and_b64 s[46:47], s[4:5], exec
	s_cselect_b32 s0, s39, s37
	s_cselect_b32 s29, s38, s36
	s_mov_b64 s[46:47], 0
	s_mov_b32 s31, -2
	v_add_u32_e32 v224, 0x10000, v184
	s_and_b64 vcc, exec, s[26:27]
	s_cbranch_vccnz .Lprio_mi
	s_setprio 1
.Lprio_mi:
	s_add_u32 s50, s46, 0x100
	s_addc_u32 s51, s47, 0
	s_add_u32 s3, s46, 0xfffff900
	s_addc_u32 s33, s47, -1
	s_cmp_gt_u32 s50, 0x7ff
	s_cselect_b32 s50, s3, s50
	s_cselect_b32 s51, s33, s51
	s_add_u32 s3, s92, s50
	s_addc_u32 s33, s93, s51
	s_add_u32 s43, s36, s50
	s_addc_u32 s54, s37, s51
	s_add_i32 s69, 0, 0x10000
	s_cmp_eq_u32 s31, 12
	s_cselect_b32 s97, s7, s33
	s_cselect_b32 s96, s11, s3
	s_cselect_b32 s95, s0, s54
	s_cselect_b32 s94, s29, s43
	s_add_i32 s3, 0, 0x14000
	ds_read_b128 v[40:43], v224
	ds_read_b128 v[60:63], v224 offset:1024
	ds_read_b128 v[80:83], v224 offset:2048
	ds_read_b128 v[100:103], v224 offset:3072
	ds_read_b128 v[120:123], v224 offset:16384
	ds_read_b128 v[140:143], v224 offset:17408
	ds_read_b128 v[152:155], v224 offset:18432
	ds_read_b128 v[168:171], v224 offset:19456
	s_add_u32 s33, s92, s46
	s_addc_u32 s43, s93, s47
	s_add_u32 s46, s33, 0x40080
	s_addc_u32 s47, s43, 0
	s_add_i32 m0, s23, 0xc000
	ds_read_b128 v[172:175], v202
	ds_read_b128 v[176:179], v202 offset:1024
	ds_read_b128 v[180:183], v202 offset:2048
	ds_read_b128 v[204:207], v202 offset:3072
	ds_read_b128 v[208:211], v202 offset:4096
	ds_read_b128 v[212:215], v202 offset:5120
	ds_read_b128 v[216:219], v202 offset:6144
	ds_read_b128 v[220:223], v202 offset:7168
	global_load_lds_dwordx4 v156, s[46:47]
	s_add_i32 m0, s23, 0xe000
	s_nop 0
	global_load_lds_dwordx4 v160, s[46:47]
	s_waitcnt vmcnt(8)
	s_waitcnt lgkmcnt(0)
	s_barrier
	s_waitcnt lgkmcnt(0)
	v_mfma_f32_16x16x32_bf16 v[148:151], v[40:43], v[172:175], 0
	v_mfma_f32_16x16x32_bf16 v[144:147], v[80:83], v[172:175], 0
	v_mfma_f32_16x16x32_bf16 v[128:131], v[40:43], v[180:183], 0
	v_mfma_f32_16x16x32_bf16 v[124:127], v[80:83], v[180:183], 0
	v_mfma_f32_16x16x32_bf16 v[108:111], v[40:43], v[208:211], 0
	v_mfma_f32_16x16x32_bf16 v[104:107], v[80:83], v[208:211], 0
	v_mfma_f32_16x16x32_bf16 v[88:91], v[40:43], v[216:219], 0
	v_mfma_f32_16x16x32_bf16 v[84:87], v[80:83], v[216:219], 0
	v_mfma_f32_16x16x32_bf16 v[148:151], v[60:63], v[176:179], v[148:151]
	v_mfma_f32_16x16x32_bf16 v[144:147], v[100:103], v[176:179], v[144:147]
	v_mfma_f32_16x16x32_bf16 v[128:131], v[60:63], v[204:207], v[128:131]
	v_mfma_f32_16x16x32_bf16 v[124:127], v[100:103], v[204:207], v[124:127]
	v_mfma_f32_16x16x32_bf16 v[108:111], v[60:63], v[212:215], v[108:111]
	v_mfma_f32_16x16x32_bf16 v[104:107], v[100:103], v[212:215], v[104:107]
	v_mfma_f32_16x16x32_bf16 v[88:91], v[60:63], v[220:223], v[88:91]
	v_mfma_f32_16x16x32_bf16 v[84:87], v[100:103], v[220:223], v[84:87]
	v_mfma_f32_16x16x32_bf16 v[136:139], v[120:123], v[172:175], 0
	v_mfma_f32_16x16x32_bf16 v[132:135], v[152:155], v[172:175], 0
	v_mfma_f32_16x16x32_bf16 v[116:119], v[120:123], v[180:183], 0
	v_mfma_f32_16x16x32_bf16 v[112:115], v[152:155], v[180:183], 0
	v_mfma_f32_16x16x32_bf16 v[96:99], v[120:123], v[208:211], 0
	v_mfma_f32_16x16x32_bf16 v[92:95], v[152:155], v[208:211], 0
	v_mfma_f32_16x16x32_bf16 v[76:79], v[120:123], v[216:219], 0
	v_mfma_f32_16x16x32_bf16 v[72:75], v[152:155], v[216:219], 0
	v_mfma_f32_16x16x32_bf16 v[136:139], v[140:143], v[176:179], v[136:139]
	v_mfma_f32_16x16x32_bf16 v[132:135], v[168:171], v[176:179], v[132:135]
	v_mfma_f32_16x16x32_bf16 v[116:119], v[140:143], v[204:207], v[116:119]
	v_mfma_f32_16x16x32_bf16 v[112:115], v[168:171], v[204:207], v[112:115]
	v_mfma_f32_16x16x32_bf16 v[96:99], v[140:143], v[212:215], v[96:99]
	v_mfma_f32_16x16x32_bf16 v[92:95], v[168:171], v[212:215], v[92:95]
	v_mfma_f32_16x16x32_bf16 v[76:79], v[140:143], v[220:223], v[76:79]
	v_mfma_f32_16x16x32_bf16 v[72:75], v[168:171], v[220:223], v[72:75]
	s_barrier
	s_add_i32 s33, s69, s60
	s_mov_b32 m0, s33
	ds_read_b128 v[172:175], v202 offset:16384
	ds_read_b128 v[176:179], v202 offset:17408
	ds_read_b128 v[180:183], v202 offset:18432
	ds_read_b128 v[204:207], v202 offset:19456
	ds_read_b128 v[208:211], v202 offset:20480
	ds_read_b128 v[212:215], v202 offset:21504
	ds_read_b128 v[216:219], v202 offset:22528
	ds_read_b128 v[220:223], v202 offset:23552
	global_load_lds_dwordx4 v158, s[94:95]
	s_add_i32 m0, s33, 0x2000
	s_add_u32 s46, s94, 0x40000
	s_addc_u32 s47, s95, 0
	s_add_i32 s3, s3, s60
	global_load_lds_dwordx4 v162, s[94:95]
	s_mov_b32 m0, s3
	s_nop 0
	global_load_lds_dwordx4 v158, s[46:47]
	s_add_i32 m0, s3, 0x2000
	s_nop 0
	global_load_lds_dwordx4 v162, s[46:47]
	s_mov_b32 m0, s23
	s_nop 0
	global_load_lds_dwordx4 v156, s[96:97]
	s_mov_b32 m0, s87
	s_nop 0
	global_load_lds_dwordx4 v160, s[96:97]
	s_waitcnt vmcnt(8)
	s_waitcnt lgkmcnt(0)
	s_barrier
	s_waitcnt lgkmcnt(0)
	v_mfma_f32_16x16x32_bf16 v[68:71], v[40:43], v[172:175], 0
	v_mfma_f32_16x16x32_bf16 v[64:67], v[80:83], v[172:175], 0
	v_mfma_f32_16x16x32_bf16 v[48:51], v[40:43], v[180:183], 0
	v_mfma_f32_16x16x32_bf16 v[44:47], v[80:83], v[180:183], 0
	v_mfma_f32_16x16x32_bf16 v[28:31], v[40:43], v[208:211], 0
	v_mfma_f32_16x16x32_bf16 v[24:27], v[80:83], v[208:211], 0
	v_mfma_f32_16x16x32_bf16 v[12:15], v[40:43], v[216:219], 0
	v_mfma_f32_16x16x32_bf16 v[8:11], v[80:83], v[216:219], 0
	v_mfma_f32_16x16x32_bf16 v[68:71], v[60:63], v[176:179], v[68:71]
	v_mfma_f32_16x16x32_bf16 v[64:67], v[100:103], v[176:179], v[64:67]
	v_mfma_f32_16x16x32_bf16 v[48:51], v[60:63], v[204:207], v[48:51]
	v_mfma_f32_16x16x32_bf16 v[44:47], v[100:103], v[204:207], v[44:47]
	v_mfma_f32_16x16x32_bf16 v[28:31], v[60:63], v[212:215], v[28:31]
	v_mfma_f32_16x16x32_bf16 v[24:27], v[100:103], v[212:215], v[24:27]
	v_mfma_f32_16x16x32_bf16 v[12:15], v[60:63], v[220:223], v[12:15]
	v_mfma_f32_16x16x32_bf16 v[8:11], v[100:103], v[220:223], v[8:11]
	v_mfma_f32_16x16x32_bf16 v[52:55], v[152:155], v[172:175], 0
	v_mfma_f32_16x16x32_bf16 v[36:39], v[120:123], v[180:183], 0
	v_mfma_f32_16x16x32_bf16 v[32:35], v[152:155], v[180:183], 0
	v_mfma_f32_16x16x32_bf16 v[20:23], v[120:123], v[208:211], 0
	v_mfma_f32_16x16x32_bf16 v[16:19], v[152:155], v[208:211], 0
	v_mfma_f32_16x16x32_bf16 v[4:7], v[120:123], v[216:219], 0
	v_mfma_f32_16x16x32_bf16 v[0:3], v[152:155], v[216:219], 0
	v_mfma_f32_16x16x32_bf16 v[40:43], v[120:123], v[172:175], 0
	v_mfma_f32_16x16x32_bf16 v[52:55], v[168:171], v[176:179], v[52:55]
	v_mfma_f32_16x16x32_bf16 v[36:39], v[140:143], v[204:207], v[36:39]
	v_mfma_f32_16x16x32_bf16 v[32:35], v[168:171], v[204:207], v[32:35]
	v_mfma_f32_16x16x32_bf16 v[20:23], v[140:143], v[212:215], v[20:23]
	v_mfma_f32_16x16x32_bf16 v[16:19], v[168:171], v[212:215], v[16:19]
	v_mfma_f32_16x16x32_bf16 v[4:7], v[140:143], v[220:223], v[4:7]
	v_mfma_f32_16x16x32_bf16 v[0:3], v[168:171], v[220:223], v[0:3]
	v_mfma_f32_16x16x32_bf16 v[40:43], v[140:143], v[176:179], v[40:43]
	s_barrier
	s_add_i32 s3, 0, 0x18000
	s_add_i32 s33, 0, 0x1c000
	ds_read_b128 v[56:59], v224 offset:32768
	ds_read_b128 v[60:63], v224 offset:33792
	ds_read_b128 v[80:83], v224 offset:34816
	ds_read_b128 v[100:103], v224 offset:35840
	ds_read_b128 v[120:123], v224 offset:49152
	ds_read_b128 v[140:143], v224 offset:50176
	ds_read_b128 v[152:155], v224 offset:51200
	ds_read_b128 v[168:171], v224 offset:52224
	s_add_u32 s46, s96, 0x40000
	s_addc_u32 s47, s97, 0
	s_mov_b32 m0, s89
	ds_read_b128 v[172:175], v202 offset:32768
	ds_read_b128 v[176:179], v202 offset:33792
	ds_read_b128 v[180:183], v202 offset:34816
	ds_read_b128 v[204:207], v202 offset:35840
	ds_read_b128 v[208:211], v202 offset:36864
	ds_read_b128 v[212:215], v202 offset:37888
	ds_read_b128 v[216:219], v202 offset:38912
	ds_read_b128 v[220:223], v202 offset:39936
	global_load_lds_dwordx4 v156, s[46:47]
	s_mov_b32 m0, s98
	s_nop 0
	global_load_lds_dwordx4 v160, s[46:47]
	s_waitcnt vmcnt(8)
	s_waitcnt lgkmcnt(0)
	s_barrier
	s_waitcnt lgkmcnt(0)
	v_mfma_f32_16x16x32_bf16 v[148:151], v[56:59], v[172:175], v[148:151]
	v_mfma_f32_16x16x32_bf16 v[144:147], v[80:83], v[172:175], v[144:147]
	v_mfma_f32_16x16x32_bf16 v[128:131], v[56:59], v[180:183], v[128:131]
	v_mfma_f32_16x16x32_bf16 v[124:127], v[80:83], v[180:183], v[124:127]
	v_mfma_f32_16x16x32_bf16 v[108:111], v[56:59], v[208:211], v[108:111]
	v_mfma_f32_16x16x32_bf16 v[104:107], v[80:83], v[208:211], v[104:107]
	v_mfma_f32_16x16x32_bf16 v[88:91], v[56:59], v[216:219], v[88:91]
	v_mfma_f32_16x16x32_bf16 v[84:87], v[80:83], v[216:219], v[84:87]
	v_mfma_f32_16x16x32_bf16 v[148:151], v[60:63], v[176:179], v[148:151]
	v_mfma_f32_16x16x32_bf16 v[144:147], v[100:103], v[176:179], v[144:147]
	v_mfma_f32_16x16x32_bf16 v[128:131], v[60:63], v[204:207], v[128:131]
	v_mfma_f32_16x16x32_bf16 v[124:127], v[100:103], v[204:207], v[124:127]
	v_mfma_f32_16x16x32_bf16 v[108:111], v[60:63], v[212:215], v[108:111]
	v_mfma_f32_16x16x32_bf16 v[104:107], v[100:103], v[212:215], v[104:107]
	v_mfma_f32_16x16x32_bf16 v[88:91], v[60:63], v[220:223], v[88:91]
	v_mfma_f32_16x16x32_bf16 v[84:87], v[100:103], v[220:223], v[84:87]
	v_mfma_f32_16x16x32_bf16 v[136:139], v[120:123], v[172:175], v[136:139]
	v_mfma_f32_16x16x32_bf16 v[132:135], v[152:155], v[172:175], v[132:135]
	v_mfma_f32_16x16x32_bf16 v[116:119], v[120:123], v[180:183], v[116:119]
	v_mfma_f32_16x16x32_bf16 v[112:115], v[152:155], v[180:183], v[112:115]
	v_mfma_f32_16x16x32_bf16 v[96:99], v[120:123], v[208:211], v[96:99]
	v_mfma_f32_16x16x32_bf16 v[92:95], v[152:155], v[208:211], v[92:95]
	v_mfma_f32_16x16x32_bf16 v[76:79], v[120:123], v[216:219], v[76:79]
	v_mfma_f32_16x16x32_bf16 v[72:75], v[152:155], v[216:219], v[72:75]
	v_mfma_f32_16x16x32_bf16 v[136:139], v[140:143], v[176:179], v[136:139]
	v_mfma_f32_16x16x32_bf16 v[132:135], v[168:171], v[176:179], v[132:135]
	v_mfma_f32_16x16x32_bf16 v[116:119], v[140:143], v[204:207], v[116:119]
	v_mfma_f32_16x16x32_bf16 v[112:115], v[168:171], v[204:207], v[112:115]
	v_mfma_f32_16x16x32_bf16 v[96:99], v[140:143], v[212:215], v[96:99]
	v_mfma_f32_16x16x32_bf16 v[92:95], v[168:171], v[212:215], v[92:95]
	v_mfma_f32_16x16x32_bf16 v[76:79], v[140:143], v[220:223], v[76:79]
	v_mfma_f32_16x16x32_bf16 v[72:75], v[168:171], v[220:223], v[72:75]
	s_barrier
	s_add_i32 s3, s3, s60
	s_add_u32 s100, s94, 0x80
	s_addc_u32 s101, s95, 0
	s_mov_b32 m0, s3
	ds_read_b128 v[172:175], v202 offset:49152
	ds_read_b128 v[176:179], v202 offset:50176
	ds_read_b128 v[180:183], v202 offset:51200
	ds_read_b128 v[204:207], v202 offset:52224
	ds_read_b128 v[208:211], v202 offset:53248
	ds_read_b128 v[212:215], v202 offset:54272
	ds_read_b128 v[216:219], v202 offset:55296
	ds_read_b128 v[220:223], v202 offset:56320
	global_load_lds_dwordx4 v158, s[100:101]
	s_add_i32 m0, s3, 0x2000
	s_add_u32 s46, s94, 0x40080
	s_addc_u32 s47, s95, 0
	s_add_i32 s3, s33, s60
	global_load_lds_dwordx4 v162, s[100:101]
	s_mov_b32 m0, s3
	s_nop 0
	global_load_lds_dwordx4 v158, s[46:47]
	s_add_i32 m0, s3, 0x2000
	s_nop 0
	global_load_lds_dwordx4 v162, s[46:47]
	s_add_u32 s100, s96, 0x80
	s_addc_u32 s101, s97, 0
	s_mov_b32 m0, s99
	s_nop 0
	global_load_lds_dwordx4 v156, s[100:101]
	s_mov_b32 m0, s16
	s_nop 0
	global_load_lds_dwordx4 v160, s[100:101]
	s_waitcnt vmcnt(8)
	s_waitcnt lgkmcnt(0)
	s_barrier
	s_waitcnt lgkmcnt(0)
	v_mfma_f32_16x16x32_bf16 v[68:71], v[56:59], v[172:175], v[68:71]
	v_mfma_f32_16x16x32_bf16 v[64:67], v[80:83], v[172:175], v[64:67]
	v_mfma_f32_16x16x32_bf16 v[48:51], v[56:59], v[180:183], v[48:51]
	v_mfma_f32_16x16x32_bf16 v[44:47], v[80:83], v[180:183], v[44:47]
	v_mfma_f32_16x16x32_bf16 v[28:31], v[56:59], v[208:211], v[28:31]
	v_mfma_f32_16x16x32_bf16 v[24:27], v[80:83], v[208:211], v[24:27]
	v_mfma_f32_16x16x32_bf16 v[12:15], v[56:59], v[216:219], v[12:15]
	v_mfma_f32_16x16x32_bf16 v[8:11], v[80:83], v[216:219], v[8:11]
	v_mfma_f32_16x16x32_bf16 v[68:71], v[60:63], v[176:179], v[68:71]
	v_mfma_f32_16x16x32_bf16 v[64:67], v[100:103], v[176:179], v[64:67]
	v_mfma_f32_16x16x32_bf16 v[48:51], v[60:63], v[204:207], v[48:51]
	v_mfma_f32_16x16x32_bf16 v[44:47], v[100:103], v[204:207], v[44:47]
	v_mfma_f32_16x16x32_bf16 v[28:31], v[60:63], v[212:215], v[28:31]
	v_mfma_f32_16x16x32_bf16 v[24:27], v[100:103], v[212:215], v[24:27]
	v_mfma_f32_16x16x32_bf16 v[12:15], v[60:63], v[220:223], v[12:15]
	v_mfma_f32_16x16x32_bf16 v[8:11], v[100:103], v[220:223], v[8:11]
	v_mfma_f32_16x16x32_bf16 v[40:43], v[120:123], v[172:175], v[40:43]
	v_mfma_f32_16x16x32_bf16 v[56:59], v[140:143], v[176:179], v[40:43]
	v_mfma_f32_16x16x32_bf16 v[40:43], v[152:155], v[172:175], v[52:55]
	v_mfma_f32_16x16x32_bf16 v[36:39], v[120:123], v[180:183], v[36:39]
	v_mfma_f32_16x16x32_bf16 v[32:35], v[152:155], v[180:183], v[32:35]
	v_mfma_f32_16x16x32_bf16 v[20:23], v[120:123], v[208:211], v[20:23]
	v_mfma_f32_16x16x32_bf16 v[16:19], v[152:155], v[208:211], v[16:19]
	v_mfma_f32_16x16x32_bf16 v[4:7], v[120:123], v[216:219], v[4:7]
	v_mfma_f32_16x16x32_bf16 v[0:3], v[152:155], v[216:219], v[0:3]
	v_mfma_f32_16x16x32_bf16 v[52:55], v[168:171], v[176:179], v[40:43]
	v_mfma_f32_16x16x32_bf16 v[36:39], v[140:143], v[204:207], v[36:39]
	v_mfma_f32_16x16x32_bf16 v[32:35], v[168:171], v[204:207], v[32:35]
	v_mfma_f32_16x16x32_bf16 v[20:23], v[140:143], v[212:215], v[20:23]
	v_mfma_f32_16x16x32_bf16 v[16:19], v[168:171], v[212:215], v[16:19]
	v_mfma_f32_16x16x32_bf16 v[4:7], v[140:143], v[220:223], v[4:7]
	v_mfma_f32_16x16x32_bf16 v[0:3], v[168:171], v[220:223], v[0:3]
	s_barrier
	s_add_i32 s31, s31, 2
	s_cmp_gt_u32 s31, 13
	s_mov_b64 s[46:47], s[50:51]
	s_cbranch_scc1 .Lpeel_exit_mixin
.LBB0_329:
	s_add_u32 s50, s46, 0x100
	s_addc_u32 s51, s47, 0
	s_add_u32 s3, s46, 0xfffff900
	s_addc_u32 s33, s47, -1
	s_cmp_gt_u32 s50, 0x7ff
	s_cselect_b32 s50, s3, s50
	s_cselect_b32 s51, s33, s51
	s_add_u32 s3, s92, s50
	s_addc_u32 s33, s93, s51
	s_add_u32 s43, s36, s50
	s_addc_u32 s54, s37, s51
	s_add_i32 s69, 0, 0x10000
	s_cmp_eq_u32 s31, 12
	s_cselect_b32 s97, s7, s33
	s_cselect_b32 s96, s11, s3
	s_cselect_b32 s95, s0, s54
	s_cselect_b32 s94, s29, s43
	s_add_i32 s3, 0, 0x14000
	ds_read_b128 v[40:43], v224
	ds_read_b128 v[60:63], v224 offset:1024
	ds_read_b128 v[80:83], v224 offset:2048
	ds_read_b128 v[100:103], v224 offset:3072
	ds_read_b128 v[120:123], v224 offset:16384
	ds_read_b128 v[140:143], v224 offset:17408
	ds_read_b128 v[152:155], v224 offset:18432
	ds_read_b128 v[168:171], v224 offset:19456
	s_add_u32 s33, s92, s46
	s_addc_u32 s43, s93, s47
	s_add_u32 s46, s33, 0x40080
	s_addc_u32 s47, s43, 0
	s_add_i32 m0, s23, 0xc000
	ds_read_b128 v[172:175], v202
	ds_read_b128 v[176:179], v202 offset:1024
	ds_read_b128 v[180:183], v202 offset:2048
	ds_read_b128 v[204:207], v202 offset:3072
	ds_read_b128 v[208:211], v202 offset:4096
	ds_read_b128 v[212:215], v202 offset:5120
	ds_read_b128 v[216:219], v202 offset:6144
	ds_read_b128 v[220:223], v202 offset:7168
	global_load_lds_dwordx4 v156, s[46:47]
	s_add_i32 m0, s23, 0xe000
	s_nop 0
	global_load_lds_dwordx4 v160, s[46:47]
	s_waitcnt vmcnt(8)
	s_waitcnt lgkmcnt(0)
	s_barrier
	s_waitcnt lgkmcnt(0)
	v_mfma_f32_16x16x32_bf16 v[148:151], v[40:43], v[172:175], v[148:151]
	v_mfma_f32_16x16x32_bf16 v[144:147], v[80:83], v[172:175], v[144:147]
	v_mfma_f32_16x16x32_bf16 v[128:131], v[40:43], v[180:183], v[128:131]
	v_mfma_f32_16x16x32_bf16 v[124:127], v[80:83], v[180:183], v[124:127]
	v_mfma_f32_16x16x32_bf16 v[108:111], v[40:43], v[208:211], v[108:111]
	v_mfma_f32_16x16x32_bf16 v[104:107], v[80:83], v[208:211], v[104:107]
	v_mfma_f32_16x16x32_bf16 v[88:91], v[40:43], v[216:219], v[88:91]
	v_mfma_f32_16x16x32_bf16 v[84:87], v[80:83], v[216:219], v[84:87]
	v_mfma_f32_16x16x32_bf16 v[148:151], v[60:63], v[176:179], v[148:151]
	v_mfma_f32_16x16x32_bf16 v[144:147], v[100:103], v[176:179], v[144:147]
	v_mfma_f32_16x16x32_bf16 v[128:131], v[60:63], v[204:207], v[128:131]
	v_mfma_f32_16x16x32_bf16 v[124:127], v[100:103], v[204:207], v[124:127]
	v_mfma_f32_16x16x32_bf16 v[108:111], v[60:63], v[212:215], v[108:111]
	v_mfma_f32_16x16x32_bf16 v[104:107], v[100:103], v[212:215], v[104:107]
	v_mfma_f32_16x16x32_bf16 v[88:91], v[60:63], v[220:223], v[88:91]
	v_mfma_f32_16x16x32_bf16 v[84:87], v[100:103], v[220:223], v[84:87]
	v_mfma_f32_16x16x32_bf16 v[136:139], v[120:123], v[172:175], v[136:139]
	v_mfma_f32_16x16x32_bf16 v[132:135], v[152:155], v[172:175], v[132:135]
	v_mfma_f32_16x16x32_bf16 v[116:119], v[120:123], v[180:183], v[116:119]
	v_mfma_f32_16x16x32_bf16 v[112:115], v[152:155], v[180:183], v[112:115]
	v_mfma_f32_16x16x32_bf16 v[96:99], v[120:123], v[208:211], v[96:99]
	v_mfma_f32_16x16x32_bf16 v[92:95], v[152:155], v[208:211], v[92:95]
	v_mfma_f32_16x16x32_bf16 v[76:79], v[120:123], v[216:219], v[76:79]
	v_mfma_f32_16x16x32_bf16 v[72:75], v[152:155], v[216:219], v[72:75]
	v_mfma_f32_16x16x32_bf16 v[136:139], v[140:143], v[176:179], v[136:139]
	v_mfma_f32_16x16x32_bf16 v[132:135], v[168:171], v[176:179], v[132:135]
	v_mfma_f32_16x16x32_bf16 v[116:119], v[140:143], v[204:207], v[116:119]
	v_mfma_f32_16x16x32_bf16 v[112:115], v[168:171], v[204:207], v[112:115]
	v_mfma_f32_16x16x32_bf16 v[96:99], v[140:143], v[212:215], v[96:99]
	v_mfma_f32_16x16x32_bf16 v[92:95], v[168:171], v[212:215], v[92:95]
	v_mfma_f32_16x16x32_bf16 v[76:79], v[140:143], v[220:223], v[76:79]
	v_mfma_f32_16x16x32_bf16 v[72:75], v[168:171], v[220:223], v[72:75]
	s_barrier
	s_add_i32 s33, s69, s60
	s_mov_b32 m0, s33
	ds_read_b128 v[172:175], v202 offset:16384
	ds_read_b128 v[176:179], v202 offset:17408
	ds_read_b128 v[180:183], v202 offset:18432
	ds_read_b128 v[204:207], v202 offset:19456
	ds_read_b128 v[208:211], v202 offset:20480
	ds_read_b128 v[212:215], v202 offset:21504
	ds_read_b128 v[216:219], v202 offset:22528
	ds_read_b128 v[220:223], v202 offset:23552
	global_load_lds_dwordx4 v158, s[94:95]
	s_add_i32 m0, s33, 0x2000
	s_add_u32 s46, s94, 0x40000
	s_addc_u32 s47, s95, 0
	s_add_i32 s3, s3, s60
	global_load_lds_dwordx4 v162, s[94:95]
	s_mov_b32 m0, s3
	s_nop 0
	global_load_lds_dwordx4 v158, s[46:47]
	s_add_i32 m0, s3, 0x2000
	s_nop 0
	global_load_lds_dwordx4 v162, s[46:47]
	s_mov_b32 m0, s23
	s_nop 0
	global_load_lds_dwordx4 v156, s[96:97]
	s_mov_b32 m0, s87
	s_nop 0
	global_load_lds_dwordx4 v160, s[96:97]
	s_waitcnt vmcnt(8)
	s_waitcnt lgkmcnt(0)
	s_barrier
	s_waitcnt lgkmcnt(0)
	v_mfma_f32_16x16x32_bf16 v[68:71], v[40:43], v[172:175], v[68:71]
	v_mfma_f32_16x16x32_bf16 v[64:67], v[80:83], v[172:175], v[64:67]
	v_mfma_f32_16x16x32_bf16 v[48:51], v[40:43], v[180:183], v[48:51]
	v_mfma_f32_16x16x32_bf16 v[44:47], v[80:83], v[180:183], v[44:47]
	v_mfma_f32_16x16x32_bf16 v[28:31], v[40:43], v[208:211], v[28:31]
	v_mfma_f32_16x16x32_bf16 v[24:27], v[80:83], v[208:211], v[24:27]
	v_mfma_f32_16x16x32_bf16 v[12:15], v[40:43], v[216:219], v[12:15]
	v_mfma_f32_16x16x32_bf16 v[8:11], v[80:83], v[216:219], v[8:11]
	v_mfma_f32_16x16x32_bf16 v[68:71], v[60:63], v[176:179], v[68:71]
	v_mfma_f32_16x16x32_bf16 v[64:67], v[100:103], v[176:179], v[64:67]
	v_mfma_f32_16x16x32_bf16 v[48:51], v[60:63], v[204:207], v[48:51]
	v_mfma_f32_16x16x32_bf16 v[44:47], v[100:103], v[204:207], v[44:47]
	v_mfma_f32_16x16x32_bf16 v[28:31], v[60:63], v[212:215], v[28:31]
	v_mfma_f32_16x16x32_bf16 v[24:27], v[100:103], v[212:215], v[24:27]
	v_mfma_f32_16x16x32_bf16 v[12:15], v[60:63], v[220:223], v[12:15]
	v_mfma_f32_16x16x32_bf16 v[8:11], v[100:103], v[220:223], v[8:11]
	v_mfma_f32_16x16x32_bf16 v[52:55], v[152:155], v[172:175], v[52:55]
	v_mfma_f32_16x16x32_bf16 v[36:39], v[120:123], v[180:183], v[36:39]
	v_mfma_f32_16x16x32_bf16 v[32:35], v[152:155], v[180:183], v[32:35]
	v_mfma_f32_16x16x32_bf16 v[20:23], v[120:123], v[208:211], v[20:23]
	v_mfma_f32_16x16x32_bf16 v[16:19], v[152:155], v[208:211], v[16:19]
	v_mfma_f32_16x16x32_bf16 v[4:7], v[120:123], v[216:219], v[4:7]
	v_mfma_f32_16x16x32_bf16 v[0:3], v[152:155], v[216:219], v[0:3]
	v_mfma_f32_16x16x32_bf16 v[40:43], v[120:123], v[172:175], v[56:59]
	v_mfma_f32_16x16x32_bf16 v[52:55], v[168:171], v[176:179], v[52:55]
	v_mfma_f32_16x16x32_bf16 v[36:39], v[140:143], v[204:207], v[36:39]
	v_mfma_f32_16x16x32_bf16 v[32:35], v[168:171], v[204:207], v[32:35]
	v_mfma_f32_16x16x32_bf16 v[20:23], v[140:143], v[212:215], v[20:23]
	v_mfma_f32_16x16x32_bf16 v[16:19], v[168:171], v[212:215], v[16:19]
	v_mfma_f32_16x16x32_bf16 v[4:7], v[140:143], v[220:223], v[4:7]
	v_mfma_f32_16x16x32_bf16 v[0:3], v[168:171], v[220:223], v[0:3]
	v_mfma_f32_16x16x32_bf16 v[40:43], v[140:143], v[176:179], v[40:43]
	s_barrier
	s_add_i32 s3, 0, 0x18000
	s_add_i32 s33, 0, 0x1c000
	ds_read_b128 v[56:59], v224 offset:32768
	ds_read_b128 v[60:63], v224 offset:33792
	ds_read_b128 v[80:83], v224 offset:34816
	ds_read_b128 v[100:103], v224 offset:35840
	ds_read_b128 v[120:123], v224 offset:49152
	ds_read_b128 v[140:143], v224 offset:50176
	ds_read_b128 v[152:155], v224 offset:51200
	ds_read_b128 v[168:171], v224 offset:52224
	s_add_u32 s46, s96, 0x40000
	s_addc_u32 s47, s97, 0
	s_mov_b32 m0, s89
	ds_read_b128 v[172:175], v202 offset:32768
	ds_read_b128 v[176:179], v202 offset:33792
	ds_read_b128 v[180:183], v202 offset:34816
	ds_read_b128 v[204:207], v202 offset:35840
	ds_read_b128 v[208:211], v202 offset:36864
	ds_read_b128 v[212:215], v202 offset:37888
	ds_read_b128 v[216:219], v202 offset:38912
	ds_read_b128 v[220:223], v202 offset:39936
	global_load_lds_dwordx4 v156, s[46:47]
	s_mov_b32 m0, s98
	s_nop 0
	global_load_lds_dwordx4 v160, s[46:47]
	s_waitcnt vmcnt(8)
	s_waitcnt lgkmcnt(0)
	s_barrier
	s_waitcnt lgkmcnt(0)
	v_mfma_f32_16x16x32_bf16 v[148:151], v[56:59], v[172:175], v[148:151]
	v_mfma_f32_16x16x32_bf16 v[144:147], v[80:83], v[172:175], v[144:147]
	v_mfma_f32_16x16x32_bf16 v[128:131], v[56:59], v[180:183], v[128:131]
	v_mfma_f32_16x16x32_bf16 v[124:127], v[80:83], v[180:183], v[124:127]
	v_mfma_f32_16x16x32_bf16 v[108:111], v[56:59], v[208:211], v[108:111]
	v_mfma_f32_16x16x32_bf16 v[104:107], v[80:83], v[208:211], v[104:107]
	v_mfma_f32_16x16x32_bf16 v[88:91], v[56:59], v[216:219], v[88:91]
	v_mfma_f32_16x16x32_bf16 v[84:87], v[80:83], v[216:219], v[84:87]
	v_mfma_f32_16x16x32_bf16 v[148:151], v[60:63], v[176:179], v[148:151]
	v_mfma_f32_16x16x32_bf16 v[144:147], v[100:103], v[176:179], v[144:147]
	v_mfma_f32_16x16x32_bf16 v[128:131], v[60:63], v[204:207], v[128:131]
	v_mfma_f32_16x16x32_bf16 v[124:127], v[100:103], v[204:207], v[124:127]
	v_mfma_f32_16x16x32_bf16 v[108:111], v[60:63], v[212:215], v[108:111]
	v_mfma_f32_16x16x32_bf16 v[104:107], v[100:103], v[212:215], v[104:107]
	v_mfma_f32_16x16x32_bf16 v[88:91], v[60:63], v[220:223], v[88:91]
	v_mfma_f32_16x16x32_bf16 v[84:87], v[100:103], v[220:223], v[84:87]
	v_mfma_f32_16x16x32_bf16 v[136:139], v[120:123], v[172:175], v[136:139]
	v_mfma_f32_16x16x32_bf16 v[132:135], v[152:155], v[172:175], v[132:135]
	v_mfma_f32_16x16x32_bf16 v[116:119], v[120:123], v[180:183], v[116:119]
	v_mfma_f32_16x16x32_bf16 v[112:115], v[152:155], v[180:183], v[112:115]
	v_mfma_f32_16x16x32_bf16 v[96:99], v[120:123], v[208:211], v[96:99]
	v_mfma_f32_16x16x32_bf16 v[92:95], v[152:155], v[208:211], v[92:95]
	v_mfma_f32_16x16x32_bf16 v[76:79], v[120:123], v[216:219], v[76:79]
	v_mfma_f32_16x16x32_bf16 v[72:75], v[152:155], v[216:219], v[72:75]
	v_mfma_f32_16x16x32_bf16 v[136:139], v[140:143], v[176:179], v[136:139]
	v_mfma_f32_16x16x32_bf16 v[132:135], v[168:171], v[176:179], v[132:135]
	v_mfma_f32_16x16x32_bf16 v[116:119], v[140:143], v[204:207], v[116:119]
	v_mfma_f32_16x16x32_bf16 v[112:115], v[168:171], v[204:207], v[112:115]
	v_mfma_f32_16x16x32_bf16 v[96:99], v[140:143], v[212:215], v[96:99]
	v_mfma_f32_16x16x32_bf16 v[92:95], v[168:171], v[212:215], v[92:95]
	v_mfma_f32_16x16x32_bf16 v[76:79], v[140:143], v[220:223], v[76:79]
	v_mfma_f32_16x16x32_bf16 v[72:75], v[168:171], v[220:223], v[72:75]
	s_barrier
	s_add_i32 s3, s3, s60
	s_add_u32 s100, s94, 0x80
	s_addc_u32 s101, s95, 0
	s_mov_b32 m0, s3
	ds_read_b128 v[172:175], v202 offset:49152
	ds_read_b128 v[176:179], v202 offset:50176
	ds_read_b128 v[180:183], v202 offset:51200
	ds_read_b128 v[204:207], v202 offset:52224
	ds_read_b128 v[208:211], v202 offset:53248
	ds_read_b128 v[212:215], v202 offset:54272
	ds_read_b128 v[216:219], v202 offset:55296
	ds_read_b128 v[220:223], v202 offset:56320
	global_load_lds_dwordx4 v158, s[100:101]
	s_add_i32 m0, s3, 0x2000
	s_add_u32 s46, s94, 0x40080
	s_addc_u32 s47, s95, 0
	s_add_i32 s3, s33, s60
	global_load_lds_dwordx4 v162, s[100:101]
	s_mov_b32 m0, s3
	s_nop 0
	global_load_lds_dwordx4 v158, s[46:47]
	s_add_i32 m0, s3, 0x2000
	s_nop 0
	global_load_lds_dwordx4 v162, s[46:47]
	s_add_u32 s100, s96, 0x80
	s_addc_u32 s101, s97, 0
	s_mov_b32 m0, s99
	s_nop 0
	global_load_lds_dwordx4 v156, s[100:101]
	s_mov_b32 m0, s16
	s_nop 0
	global_load_lds_dwordx4 v160, s[100:101]
	s_waitcnt vmcnt(8)
	s_waitcnt lgkmcnt(0)
	s_barrier
	s_waitcnt lgkmcnt(0)
	v_mfma_f32_16x16x32_bf16 v[68:71], v[56:59], v[172:175], v[68:71]
	v_mfma_f32_16x16x32_bf16 v[64:67], v[80:83], v[172:175], v[64:67]
	v_mfma_f32_16x16x32_bf16 v[48:51], v[56:59], v[180:183], v[48:51]
	v_mfma_f32_16x16x32_bf16 v[44:47], v[80:83], v[180:183], v[44:47]
	v_mfma_f32_16x16x32_bf16 v[28:31], v[56:59], v[208:211], v[28:31]
	v_mfma_f32_16x16x32_bf16 v[24:27], v[80:83], v[208:211], v[24:27]
	v_mfma_f32_16x16x32_bf16 v[12:15], v[56:59], v[216:219], v[12:15]
	v_mfma_f32_16x16x32_bf16 v[8:11], v[80:83], v[216:219], v[8:11]
	v_mfma_f32_16x16x32_bf16 v[68:71], v[60:63], v[176:179], v[68:71]
	v_mfma_f32_16x16x32_bf16 v[64:67], v[100:103], v[176:179], v[64:67]
	v_mfma_f32_16x16x32_bf16 v[48:51], v[60:63], v[204:207], v[48:51]
	v_mfma_f32_16x16x32_bf16 v[44:47], v[100:103], v[204:207], v[44:47]
	v_mfma_f32_16x16x32_bf16 v[28:31], v[60:63], v[212:215], v[28:31]
	v_mfma_f32_16x16x32_bf16 v[24:27], v[100:103], v[212:215], v[24:27]
	v_mfma_f32_16x16x32_bf16 v[12:15], v[60:63], v[220:223], v[12:15]
	v_mfma_f32_16x16x32_bf16 v[8:11], v[100:103], v[220:223], v[8:11]
	v_mfma_f32_16x16x32_bf16 v[40:43], v[120:123], v[172:175], v[40:43]
	v_mfma_f32_16x16x32_bf16 v[56:59], v[140:143], v[176:179], v[40:43]
	v_mfma_f32_16x16x32_bf16 v[40:43], v[152:155], v[172:175], v[52:55]
	v_mfma_f32_16x16x32_bf16 v[36:39], v[120:123], v[180:183], v[36:39]
	v_mfma_f32_16x16x32_bf16 v[32:35], v[152:155], v[180:183], v[32:35]
	v_mfma_f32_16x16x32_bf16 v[20:23], v[120:123], v[208:211], v[20:23]
	v_mfma_f32_16x16x32_bf16 v[16:19], v[152:155], v[208:211], v[16:19]
	v_mfma_f32_16x16x32_bf16 v[4:7], v[120:123], v[216:219], v[4:7]
	v_mfma_f32_16x16x32_bf16 v[0:3], v[152:155], v[216:219], v[0:3]
	v_mfma_f32_16x16x32_bf16 v[52:55], v[168:171], v[176:179], v[40:43]
	v_mfma_f32_16x16x32_bf16 v[36:39], v[140:143], v[204:207], v[36:39]
	v_mfma_f32_16x16x32_bf16 v[32:35], v[168:171], v[204:207], v[32:35]
	v_mfma_f32_16x16x32_bf16 v[20:23], v[140:143], v[212:215], v[20:23]
	v_mfma_f32_16x16x32_bf16 v[16:19], v[168:171], v[212:215], v[16:19]
	v_mfma_f32_16x16x32_bf16 v[4:7], v[140:143], v[220:223], v[4:7]
	v_mfma_f32_16x16x32_bf16 v[0:3], v[168:171], v[220:223], v[0:3]
	s_barrier
	s_add_i32 s31, s31, 2
	s_cmp_gt_u32 s31, 13
	s_mov_b64 s[46:47], s[50:51]
	s_cbranch_scc0 .LBB0_329

.LBB0_332:
	s_setprio 0
	v_lshl_add_u32 v168, s1, 12, v186
	ds_read_b128 v[40:43], v168
	ds_read_b128 v[152:155], v168 offset:256
	v_lshl_or_b32 v188, s22, 8, v187
	s_waitcnt lgkmcnt(0)
	v_mov_b32_e32 v60, v41
	v_mov_b32_e32 v61, v42
	v_mov_b32_e32 v41, v43
	v_pk_add_f32 v[40:41], v[60:61], v[40:41]
	s_nop 0
	v_add_f32_e32 v40, v40, v41
	v_fmamk_f32 v169, v40, 0x3a800000, v229
	ds_read_b128 v[140:143], v168 offset:512
	ds_read_b128 v[120:123], v168 offset:768
	ds_read_b128 v[100:103], v168 offset:2048
	ds_read_b128 v[80:83], v168 offset:2304
	ds_read_b128 v[60:63], v168 offset:2560
	ds_read_b128 v[40:43], v168 offset:2816
	v_rsq_f32_e32 v172, v169
	v_lshl_add_u32 v168, s6, 8, v165
	v_ashrrev_i32_e32 v169, 31, v168
	s_cmp_gt_i32 s22, 1
	v_lshlrev_b64 v[170:171], 10, v[168:169]
	v_pk_mul_f32 v[148:149], v[148:149], v[172:173] op_sel_hi:[1,0]
	v_pk_mul_f32 v[150:151], v[150:151], v[172:173] op_sel_hi:[1,0]
	v_pk_mul_f32 v[144:145], v[144:145], v[172:173] op_sel_hi:[1,0]
	v_pk_mul_f32 v[146:147], v[146:147], v[172:173] op_sel_hi:[1,0]
	s_cselect_b64 s[36:37], -1, 0
	s_cmp_lt_i32 s22, 2
	s_mov_b64 s[6:7], -1
	s_mov_b64 s[50:51], 0x100
	s_cbranch_scc1 .LBB0_338
	v_pk_mul_f32 v[176:177], v[150:151], v[150:151]
	v_pk_mul_f32 v[174:175], v[148:149], v[148:149]
	v_pk_fma_f32 v[176:177], v[176:177], s[64:65], 1.0 op_sel_hi:[1,0,0]
	v_pk_mul_f32 v[180:181], v[146:147], v[146:147]
	v_pk_mul_f32 v[176:177], v[150:151], v[176:177]
	v_pk_fma_f32 v[174:175], v[174:175], s[64:65], 1.0 op_sel_hi:[1,0,0]
	v_pk_mul_f32 v[176:177], v[176:177], s[66:67] op_sel_hi:[1,0]
	v_pk_fma_f32 v[180:181], v[180:181], s[64:65], 1.0 op_sel_hi:[1,0,0]
	v_pk_mul_f32 v[176:177], v[176:177], s[68:69] op_sel_hi:[1,0]
	v_pk_mul_f32 v[174:175], v[148:149], v[174:175]
	v_exp_f32_e32 v176, v176
	v_exp_f32_e32 v177, v177
	v_pk_mul_f32 v[180:181], v[146:147], v[180:181]
	v_pk_mul_f32 v[174:175], v[174:175], s[66:67] op_sel_hi:[1,0]
	v_pk_mul_f32 v[180:181], v[180:181], s[66:67] op_sel_hi:[1,0]
	v_pk_add_f32 v[176:177], v[176:177], 1.0 op_sel_hi:[1,0]
	v_pk_mul_f32 v[174:175], v[174:175], s[68:69] op_sel_hi:[1,0]
	v_rcp_f32_e32 v178, v176
	v_rcp_f32_e32 v179, v177
	v_pk_mul_f32 v[176:177], v[144:145], v[144:145]
	v_pk_mul_f32 v[180:181], v[180:181], s[68:69] op_sel_hi:[1,0]
	v_pk_fma_f32 v[176:177], v[176:177], s[64:65], 1.0 op_sel_hi:[1,0,0]
	v_exp_f32_e32 v174, v174
	v_pk_mul_f32 v[176:177], v[144:145], v[176:177]
	v_exp_f32_e32 v175, v175
	v_pk_mul_f32 v[176:177], v[176:177], s[66:67] op_sel_hi:[1,0]
	v_exp_f32_e32 v180, v180
	v_pk_mul_f32 v[176:177], v[176:177], s[68:69] op_sel_hi:[1,0]
	v_exp_f32_e32 v181, v181
	v_exp_f32_e32 v176, v176
	v_exp_f32_e32 v177, v177
	v_pk_add_f32 v[174:175], v[174:175], 1.0 op_sel_hi:[1,0]
	v_pk_mul_f32 v[178:179], v[150:151], v[178:179]
	v_rcp_f32_e32 v174, v174
	v_pk_add_f32 v[176:177], v[176:177], 1.0 op_sel_hi:[1,0]
	v_rcp_f32_e32 v175, v175
	v_rcp_f32_e32 v182, v176
	v_rcp_f32_e32 v183, v177
	v_pk_add_f32 v[176:177], v[180:181], 1.0 op_sel_hi:[1,0]
	s_cmp_gt_u32 s22, 3
	v_rcp_f32_e32 v204, v176
	v_rcp_f32_e32 v205, v177
	v_pk_mul_f32 v[176:177], v[148:149], v[174:175]
	v_pk_mul_f32 v[180:181], v[144:145], v[182:183]
	v_pk_mul_f32 v[174:175], v[146:147], v[204:205]
	s_cbranch_scc0 .LBB0_335
	v_lshl_add_u64 v[182:183], s[20:21], 0, v[170:171]
	s_movk_i32 s0, 0xf800
	v_lshl_add_u64 v[182:183], v[188:189], 1, v[182:183]
	s_mov_b32 s1, -1
	v_lshl_add_u64 v[182:183], v[182:183], 0, s[0:1]
	s_mov_b64 s[6:7], 0

.LBB0_489:
	s_add_u32 s0, s34, s92
	s_addc_u32 s43, s35, 0
	s_mov_b64 s[36:37], 0
	s_mov_b32 s86, 0
	v_add_u32_e32 v212, 0x10000, v234
	s_and_b64 vcc, exec, s[26:27]
	s_cbranch_vccnz .Lprio_re
	s_setprio 1
.Lprio_re:
	s_add_u32 s38, s36, 0x100
	s_addc_u32 s39, s37, 0
	s_cmp_ge_u32 s38, s24
	s_cselect_b32 s47, s24, 0
	s_cselect_b32 s46, 0, 0
	s_sub_u32 s38, s38, s47
	s_subb_u32 s39, s39, s46
	s_sub_u32 s47, s36, s47
	s_subb_u32 s46, s37, s46
	s_add_u32 vcc_lo, s34, s47
	s_addc_u32 vcc_hi, s35, s46
	s_add_u32 vcc_lo, vcc_lo, 0x100
	s_addc_u32 vcc_hi, vcc_hi, 0
	s_add_u32 s47, s30, s47
	s_addc_u32 s46, s31, s46
	s_add_u32 s69, s47, 0x100
	s_addc_u32 s3, s46, 0
	s_add_i32 s33, 0, 0x10000
	s_cmp_eq_u32 s99, s86
	s_cselect_b32 s47, s11, vcc_hi
	s_cselect_b32 s46, s10, vcc_lo
	s_cselect_b32 vcc_hi, s29, s3
	s_cselect_b32 vcc_lo, s28, s69
	s_add_i32 s3, 0, 0x14000
	ds_read_b128 v[120:123], v212
	ds_read_b128 v[124:127], v212 offset:1024
	ds_read_b128 v[128:131], v212 offset:2048
	ds_read_b128 v[132:135], v212 offset:3072
	ds_read_b128 v[136:139], v212 offset:16384
	ds_read_b128 v[140:143], v212 offset:17408
	ds_read_b128 v[144:147], v212 offset:18432
	ds_read_b128 v[148:151], v212 offset:19456
	s_add_u32 s36, s0, s36
	s_addc_u32 s37, s43, s37
	s_add_u32 s100, s36, 0x80
	s_addc_u32 s101, s37, 0
	s_add_i32 m0, s94, 0xc000
	ds_read_b128 v[152:155], v248
	ds_read_b128 v[156:159], v248 offset:1024
	ds_read_b128 v[160:163], v248 offset:2048
	ds_read_b128 v[172:175], v248 offset:3072
	ds_read_b128 v[176:179], v248 offset:4096
	ds_read_b128 v[180:183], v248 offset:5120
	ds_read_b128 v[184:187], v248 offset:6144
	ds_read_b128 v[208:211], v248 offset:7168
	global_load_lds_dwordx4 v202, s[100:101]
	s_add_i32 m0, s94, 0xe000
	s_nop 0
	global_load_lds_dwordx4 v204, s[100:101]
	s_waitcnt vmcnt(8)
	s_waitcnt lgkmcnt(0)
	s_barrier
	s_waitcnt lgkmcnt(0)
	v_mfma_f32_16x16x32_bf16 v[168:171], v[120:123], v[152:155], 0
	v_mfma_f32_16x16x32_bf16 v[164:167], v[128:131], v[152:155], 0
	v_mfma_f32_16x16x32_bf16 v[108:111], v[120:123], v[160:163], 0
	v_mfma_f32_16x16x32_bf16 v[104:107], v[128:131], v[160:163], 0
	v_mfma_f32_16x16x32_bf16 v[92:95], v[120:123], v[176:179], 0
	v_mfma_f32_16x16x32_bf16 v[88:91], v[128:131], v[176:179], 0
	v_mfma_f32_16x16x32_bf16 v[76:79], v[120:123], v[184:187], 0
	v_mfma_f32_16x16x32_bf16 v[72:75], v[128:131], v[184:187], 0
	v_mfma_f32_16x16x32_bf16 v[168:171], v[124:127], v[156:159], v[168:171]
	v_mfma_f32_16x16x32_bf16 v[164:167], v[132:135], v[156:159], v[164:167]
	v_mfma_f32_16x16x32_bf16 v[108:111], v[124:127], v[172:175], v[108:111]
	v_mfma_f32_16x16x32_bf16 v[104:107], v[132:135], v[172:175], v[104:107]
	v_mfma_f32_16x16x32_bf16 v[92:95], v[124:127], v[180:183], v[92:95]
	v_mfma_f32_16x16x32_bf16 v[88:91], v[132:135], v[180:183], v[88:91]
	v_mfma_f32_16x16x32_bf16 v[76:79], v[124:127], v[208:211], v[76:79]
	v_mfma_f32_16x16x32_bf16 v[72:75], v[132:135], v[208:211], v[72:75]
	v_mfma_f32_16x16x32_bf16 v[116:119], v[136:139], v[152:155], 0
	v_mfma_f32_16x16x32_bf16 v[112:115], v[144:147], v[152:155], 0
	v_mfma_f32_16x16x32_bf16 v[100:103], v[136:139], v[160:163], 0
	v_mfma_f32_16x16x32_bf16 v[96:99], v[144:147], v[160:163], 0
	v_mfma_f32_16x16x32_bf16 v[84:87], v[136:139], v[176:179], 0
	v_mfma_f32_16x16x32_bf16 v[80:83], v[144:147], v[176:179], 0
	v_mfma_f32_16x16x32_bf16 v[68:71], v[136:139], v[184:187], 0
	v_mfma_f32_16x16x32_bf16 v[64:67], v[144:147], v[184:187], 0
	v_mfma_f32_16x16x32_bf16 v[116:119], v[140:143], v[156:159], v[116:119]
	v_mfma_f32_16x16x32_bf16 v[112:115], v[148:151], v[156:159], v[112:115]
	v_mfma_f32_16x16x32_bf16 v[100:103], v[140:143], v[172:175], v[100:103]
	v_mfma_f32_16x16x32_bf16 v[96:99], v[148:151], v[172:175], v[96:99]
	v_mfma_f32_16x16x32_bf16 v[84:87], v[140:143], v[180:183], v[84:87]
	v_mfma_f32_16x16x32_bf16 v[80:83], v[148:151], v[180:183], v[80:83]
	v_mfma_f32_16x16x32_bf16 v[68:71], v[140:143], v[208:211], v[68:71]
	v_mfma_f32_16x16x32_bf16 v[64:67], v[148:151], v[208:211], v[64:67]
	s_barrier
	s_add_i32 s33, s33, s89
	s_mov_b64 s[100:101], vcc
	s_mov_b32 m0, s33
	ds_read_b128 v[152:155], v248 offset:16384
	ds_read_b128 v[156:159], v248 offset:17408
	ds_read_b128 v[160:163], v248 offset:18432
	ds_read_b128 v[172:175], v248 offset:19456
	ds_read_b128 v[176:179], v248 offset:20480
	ds_read_b128 v[180:183], v248 offset:21504
	ds_read_b128 v[184:187], v248 offset:22528
	ds_read_b128 v[208:211], v248 offset:23552
	global_load_lds_dwordx4 v188, s[100:101]
	s_add_i32 m0, s33, 0x2000
	s_add_u32 s36, vcc_lo, s92
	s_addc_u32 s37, vcc_hi, 0
	s_add_i32 s3, s3, s89
	global_load_lds_dwordx4 v206, s[100:101]
	s_mov_b32 m0, s3
	s_nop 0
	global_load_lds_dwordx4 v188, s[36:37]
	s_add_i32 m0, s3, 0x2000
	s_nop 0
	global_load_lds_dwordx4 v206, s[36:37]
	s_mov_b32 m0, s94
	s_nop 0
	global_load_lds_dwordx4 v202, s[46:47]
	s_mov_b32 m0, s95
	s_nop 0
	global_load_lds_dwordx4 v204, s[46:47]
	s_waitcnt vmcnt(8)
	s_waitcnt lgkmcnt(0)
	s_barrier
	s_waitcnt lgkmcnt(0)
	v_mfma_f32_16x16x32_bf16 v[60:63], v[120:123], v[152:155], 0
	v_mfma_f32_16x16x32_bf16 v[56:59], v[128:131], v[152:155], 0
	v_mfma_f32_16x16x32_bf16 v[44:47], v[120:123], v[160:163], 0
	v_mfma_f32_16x16x32_bf16 v[40:43], v[128:131], v[160:163], 0
	v_mfma_f32_16x16x32_bf16 v[28:31], v[120:123], v[176:179], 0
	v_mfma_f32_16x16x32_bf16 v[24:27], v[128:131], v[176:179], 0
	v_mfma_f32_16x16x32_bf16 v[12:15], v[120:123], v[184:187], 0
	v_mfma_f32_16x16x32_bf16 v[8:11], v[128:131], v[184:187], 0
	v_mfma_f32_16x16x32_bf16 v[60:63], v[124:127], v[156:159], v[60:63]
	v_mfma_f32_16x16x32_bf16 v[56:59], v[132:135], v[156:159], v[56:59]
	v_mfma_f32_16x16x32_bf16 v[44:47], v[124:127], v[172:175], v[44:47]
	v_mfma_f32_16x16x32_bf16 v[40:43], v[132:135], v[172:175], v[40:43]
	v_mfma_f32_16x16x32_bf16 v[28:31], v[124:127], v[180:183], v[28:31]
	v_mfma_f32_16x16x32_bf16 v[24:27], v[132:135], v[180:183], v[24:27]
	v_mfma_f32_16x16x32_bf16 v[12:15], v[124:127], v[208:211], v[12:15]
	v_mfma_f32_16x16x32_bf16 v[8:11], v[132:135], v[208:211], v[8:11]
	v_mfma_f32_16x16x32_bf16 v[52:55], v[136:139], v[152:155], 0
	v_mfma_f32_16x16x32_bf16 v[48:51], v[144:147], v[152:155], 0
	v_mfma_f32_16x16x32_bf16 v[36:39], v[136:139], v[160:163], 0
	v_mfma_f32_16x16x32_bf16 v[32:35], v[144:147], v[160:163], 0
	v_mfma_f32_16x16x32_bf16 v[20:23], v[136:139], v[176:179], 0
	v_mfma_f32_16x16x32_bf16 v[16:19], v[144:147], v[176:179], 0
	v_mfma_f32_16x16x32_bf16 v[4:7], v[136:139], v[184:187], 0
	v_mfma_f32_16x16x32_bf16 v[0:3], v[144:147], v[184:187], 0
	v_mfma_f32_16x16x32_bf16 v[52:55], v[140:143], v[156:159], v[52:55]
	v_mfma_f32_16x16x32_bf16 v[48:51], v[148:151], v[156:159], v[48:51]
	v_mfma_f32_16x16x32_bf16 v[36:39], v[140:143], v[172:175], v[36:39]
	v_mfma_f32_16x16x32_bf16 v[32:35], v[148:151], v[172:175], v[32:35]
	v_mfma_f32_16x16x32_bf16 v[20:23], v[140:143], v[180:183], v[20:23]
	v_mfma_f32_16x16x32_bf16 v[16:19], v[148:151], v[180:183], v[16:19]
	v_mfma_f32_16x16x32_bf16 v[4:7], v[140:143], v[208:211], v[4:7]
	v_mfma_f32_16x16x32_bf16 v[0:3], v[148:151], v[208:211], v[0:3]
	s_barrier
	s_add_i32 s3, 0, 0x18000
	s_add_i32 s33, 0, 0x1c000
	ds_read_b128 v[120:123], v212 offset:32768
	ds_read_b128 v[124:127], v212 offset:33792
	ds_read_b128 v[128:131], v212 offset:34816
	ds_read_b128 v[132:135], v212 offset:35840
	ds_read_b128 v[136:139], v212 offset:49152
	ds_read_b128 v[140:143], v212 offset:50176
	ds_read_b128 v[144:147], v212 offset:51200
	ds_read_b128 v[148:151], v212 offset:52224
	s_add_u32 s36, s46, s92
	s_addc_u32 s37, s47, 0
	s_mov_b32 m0, s96
	ds_read_b128 v[152:155], v248 offset:32768
	ds_read_b128 v[156:159], v248 offset:33792
	ds_read_b128 v[160:163], v248 offset:34816
	ds_read_b128 v[172:175], v248 offset:35840
	ds_read_b128 v[176:179], v248 offset:36864
	ds_read_b128 v[180:183], v248 offset:37888
	ds_read_b128 v[184:187], v248 offset:38912
	ds_read_b128 v[208:211], v248 offset:39936
	global_load_lds_dwordx4 v202, s[36:37]
	s_mov_b32 m0, s97
	s_nop 0
	global_load_lds_dwordx4 v204, s[36:37]
	s_waitcnt vmcnt(8)
	s_waitcnt lgkmcnt(0)
	s_barrier
	s_waitcnt lgkmcnt(0)
	v_mfma_f32_16x16x32_bf16 v[168:171], v[120:123], v[152:155], v[168:171]
	v_mfma_f32_16x16x32_bf16 v[164:167], v[128:131], v[152:155], v[164:167]
	v_mfma_f32_16x16x32_bf16 v[108:111], v[120:123], v[160:163], v[108:111]
	v_mfma_f32_16x16x32_bf16 v[104:107], v[128:131], v[160:163], v[104:107]
	v_mfma_f32_16x16x32_bf16 v[92:95], v[120:123], v[176:179], v[92:95]
	v_mfma_f32_16x16x32_bf16 v[88:91], v[128:131], v[176:179], v[88:91]
	v_mfma_f32_16x16x32_bf16 v[76:79], v[120:123], v[184:187], v[76:79]
	v_mfma_f32_16x16x32_bf16 v[72:75], v[128:131], v[184:187], v[72:75]
	v_mfma_f32_16x16x32_bf16 v[168:171], v[124:127], v[156:159], v[168:171]
	v_mfma_f32_16x16x32_bf16 v[164:167], v[132:135], v[156:159], v[164:167]
	v_mfma_f32_16x16x32_bf16 v[108:111], v[124:127], v[172:175], v[108:111]
	v_mfma_f32_16x16x32_bf16 v[104:107], v[132:135], v[172:175], v[104:107]
	v_mfma_f32_16x16x32_bf16 v[92:95], v[124:127], v[180:183], v[92:95]
	v_mfma_f32_16x16x32_bf16 v[88:91], v[132:135], v[180:183], v[88:91]
	v_mfma_f32_16x16x32_bf16 v[76:79], v[124:127], v[208:211], v[76:79]
	v_mfma_f32_16x16x32_bf16 v[72:75], v[132:135], v[208:211], v[72:75]
	v_mfma_f32_16x16x32_bf16 v[116:119], v[136:139], v[152:155], v[116:119]
	v_mfma_f32_16x16x32_bf16 v[112:115], v[144:147], v[152:155], v[112:115]
	v_mfma_f32_16x16x32_bf16 v[100:103], v[136:139], v[160:163], v[100:103]
	v_mfma_f32_16x16x32_bf16 v[96:99], v[144:147], v[160:163], v[96:99]
	v_mfma_f32_16x16x32_bf16 v[84:87], v[136:139], v[176:179], v[84:87]
	v_mfma_f32_16x16x32_bf16 v[80:83], v[144:147], v[176:179], v[80:83]
	v_mfma_f32_16x16x32_bf16 v[68:71], v[136:139], v[184:187], v[68:71]
	v_mfma_f32_16x16x32_bf16 v[64:67], v[144:147], v[184:187], v[64:67]
	v_mfma_f32_16x16x32_bf16 v[116:119], v[140:143], v[156:159], v[116:119]
	v_mfma_f32_16x16x32_bf16 v[112:115], v[148:151], v[156:159], v[112:115]
	v_mfma_f32_16x16x32_bf16 v[100:103], v[140:143], v[172:175], v[100:103]
	v_mfma_f32_16x16x32_bf16 v[96:99], v[148:151], v[172:175], v[96:99]
	v_mfma_f32_16x16x32_bf16 v[84:87], v[140:143], v[180:183], v[84:87]
	v_mfma_f32_16x16x32_bf16 v[80:83], v[148:151], v[180:183], v[80:83]
	v_mfma_f32_16x16x32_bf16 v[68:71], v[140:143], v[208:211], v[68:71]
	v_mfma_f32_16x16x32_bf16 v[64:67], v[148:151], v[208:211], v[64:67]
	s_barrier
	s_add_i32 s3, s3, s89
	s_add_u32 s100, vcc_lo, 0x80
	s_addc_u32 s101, vcc_hi, 0
	s_mov_b32 m0, s3
	ds_read_b128 v[152:155], v248 offset:49152
	ds_read_b128 v[156:159], v248 offset:50176
	ds_read_b128 v[160:163], v248 offset:51200
	ds_read_b128 v[172:175], v248 offset:52224
	ds_read_b128 v[176:179], v248 offset:53248
	ds_read_b128 v[180:183], v248 offset:54272
	ds_read_b128 v[184:187], v248 offset:55296
	ds_read_b128 v[208:211], v248 offset:56320
	global_load_lds_dwordx4 v188, s[100:101]
	s_add_i32 m0, s3, 0x2000
	s_add_i32 s3, s33, s89
	global_load_lds_dwordx4 v206, s[100:101]
	s_add_u32 s36, s100, s92
	s_addc_u32 s37, s101, 0
	s_mov_b32 m0, s3
	s_nop 0
	global_load_lds_dwordx4 v188, s[36:37]
	s_add_i32 m0, s3, 0x2000
	s_nop 0
	global_load_lds_dwordx4 v206, s[36:37]
	s_add_u32 s100, s46, 0x80
	s_addc_u32 s101, s47, 0
	s_mov_b32 m0, s76
	s_nop 0
	global_load_lds_dwordx4 v202, s[100:101]
	s_mov_b32 m0, s77
	s_nop 0
	global_load_lds_dwordx4 v204, s[100:101]
	s_waitcnt vmcnt(8)
	s_waitcnt lgkmcnt(0)
	s_barrier
	s_waitcnt lgkmcnt(0)
	v_mfma_f32_16x16x32_bf16 v[60:63], v[120:123], v[152:155], v[60:63]
	v_mfma_f32_16x16x32_bf16 v[56:59], v[128:131], v[152:155], v[56:59]
	v_mfma_f32_16x16x32_bf16 v[44:47], v[120:123], v[160:163], v[44:47]
	v_mfma_f32_16x16x32_bf16 v[40:43], v[128:131], v[160:163], v[40:43]
	v_mfma_f32_16x16x32_bf16 v[28:31], v[120:123], v[176:179], v[28:31]
	v_mfma_f32_16x16x32_bf16 v[24:27], v[128:131], v[176:179], v[24:27]
	v_mfma_f32_16x16x32_bf16 v[12:15], v[120:123], v[184:187], v[12:15]
	v_mfma_f32_16x16x32_bf16 v[8:11], v[128:131], v[184:187], v[8:11]
	v_mfma_f32_16x16x32_bf16 v[60:63], v[124:127], v[156:159], v[60:63]
	v_mfma_f32_16x16x32_bf16 v[56:59], v[132:135], v[156:159], v[56:59]
	v_mfma_f32_16x16x32_bf16 v[44:47], v[124:127], v[172:175], v[44:47]
	v_mfma_f32_16x16x32_bf16 v[40:43], v[132:135], v[172:175], v[40:43]
	v_mfma_f32_16x16x32_bf16 v[28:31], v[124:127], v[180:183], v[28:31]
	v_mfma_f32_16x16x32_bf16 v[24:27], v[132:135], v[180:183], v[24:27]
	v_mfma_f32_16x16x32_bf16 v[12:15], v[124:127], v[208:211], v[12:15]
	v_mfma_f32_16x16x32_bf16 v[8:11], v[132:135], v[208:211], v[8:11]
	v_mfma_f32_16x16x32_bf16 v[52:55], v[136:139], v[152:155], v[52:55]
	v_mfma_f32_16x16x32_bf16 v[48:51], v[144:147], v[152:155], v[48:51]
	v_mfma_f32_16x16x32_bf16 v[36:39], v[136:139], v[160:163], v[36:39]
	v_mfma_f32_16x16x32_bf16 v[32:35], v[144:147], v[160:163], v[32:35]
	v_mfma_f32_16x16x32_bf16 v[20:23], v[136:139], v[176:179], v[20:23]
	v_mfma_f32_16x16x32_bf16 v[16:19], v[144:147], v[176:179], v[16:19]
	v_mfma_f32_16x16x32_bf16 v[4:7], v[136:139], v[184:187], v[4:7]
	v_mfma_f32_16x16x32_bf16 v[0:3], v[144:147], v[184:187], v[0:3]
	v_mfma_f32_16x16x32_bf16 v[52:55], v[140:143], v[156:159], v[52:55]
	v_mfma_f32_16x16x32_bf16 v[48:51], v[148:151], v[156:159], v[48:51]
	v_mfma_f32_16x16x32_bf16 v[36:39], v[140:143], v[172:175], v[36:39]
	v_mfma_f32_16x16x32_bf16 v[32:35], v[148:151], v[172:175], v[32:35]
	v_mfma_f32_16x16x32_bf16 v[20:23], v[140:143], v[180:183], v[20:23]
	v_mfma_f32_16x16x32_bf16 v[16:19], v[148:151], v[180:183], v[16:19]
	v_mfma_f32_16x16x32_bf16 v[4:7], v[140:143], v[208:211], v[4:7]
	v_mfma_f32_16x16x32_bf16 v[0:3], v[148:151], v[208:211], v[0:3]
	s_barrier
	s_add_i32 s86, s86, 2
	s_cmp_ge_u32 s86, s98
	s_mov_b64 s[36:37], s[38:39]
	s_cbranch_scc1 .Lpeel_exit_resid
.LBB0_490:
	s_add_u32 s38, s36, 0x100
	s_addc_u32 s39, s37, 0
	s_cmp_ge_u32 s38, s24
	s_cselect_b32 s47, s24, 0
	s_cselect_b32 s46, 0, 0
	s_sub_u32 s38, s38, s47
	s_subb_u32 s39, s39, s46
	s_sub_u32 s47, s36, s47
	s_subb_u32 s46, s37, s46
	s_add_u32 vcc_lo, s34, s47
	s_addc_u32 vcc_hi, s35, s46
	s_add_u32 vcc_lo, vcc_lo, 0x100
	s_addc_u32 vcc_hi, vcc_hi, 0
	s_add_u32 s47, s30, s47
	s_addc_u32 s46, s31, s46
	s_add_u32 s69, s47, 0x100
	s_addc_u32 s3, s46, 0
	s_add_i32 s33, 0, 0x10000
	s_cmp_eq_u32 s99, s86
	s_cselect_b32 s47, s11, vcc_hi
	s_cselect_b32 s46, s10, vcc_lo
	s_cselect_b32 vcc_hi, s29, s3
	s_cselect_b32 vcc_lo, s28, s69
	s_add_i32 s3, 0, 0x14000
	ds_read_b128 v[120:123], v212
	ds_read_b128 v[124:127], v212 offset:1024
	ds_read_b128 v[128:131], v212 offset:2048
	ds_read_b128 v[132:135], v212 offset:3072
	ds_read_b128 v[136:139], v212 offset:16384
	ds_read_b128 v[140:143], v212 offset:17408
	ds_read_b128 v[144:147], v212 offset:18432
	ds_read_b128 v[148:151], v212 offset:19456
	s_add_u32 s36, s0, s36
	s_addc_u32 s37, s43, s37
	s_add_u32 s100, s36, 0x80
	s_addc_u32 s101, s37, 0
	s_add_i32 m0, s94, 0xc000
	ds_read_b128 v[152:155], v248
	ds_read_b128 v[156:159], v248 offset:1024
	ds_read_b128 v[160:163], v248 offset:2048
	ds_read_b128 v[172:175], v248 offset:3072
	ds_read_b128 v[176:179], v248 offset:4096
	ds_read_b128 v[180:183], v248 offset:5120
	ds_read_b128 v[184:187], v248 offset:6144
	ds_read_b128 v[208:211], v248 offset:7168
	global_load_lds_dwordx4 v202, s[100:101]
	s_add_i32 m0, s94, 0xe000
	s_nop 0
	global_load_lds_dwordx4 v204, s[100:101]
	s_waitcnt vmcnt(8)
	s_waitcnt lgkmcnt(0)
	s_barrier
	s_waitcnt lgkmcnt(0)
	v_mfma_f32_16x16x32_bf16 v[168:171], v[120:123], v[152:155], v[168:171]
	v_mfma_f32_16x16x32_bf16 v[164:167], v[128:131], v[152:155], v[164:167]
	v_mfma_f32_16x16x32_bf16 v[108:111], v[120:123], v[160:163], v[108:111]
	v_mfma_f32_16x16x32_bf16 v[104:107], v[128:131], v[160:163], v[104:107]
	v_mfma_f32_16x16x32_bf16 v[92:95], v[120:123], v[176:179], v[92:95]
	v_mfma_f32_16x16x32_bf16 v[88:91], v[128:131], v[176:179], v[88:91]
	v_mfma_f32_16x16x32_bf16 v[76:79], v[120:123], v[184:187], v[76:79]
	v_mfma_f32_16x16x32_bf16 v[72:75], v[128:131], v[184:187], v[72:75]
	v_mfma_f32_16x16x32_bf16 v[168:171], v[124:127], v[156:159], v[168:171]
	v_mfma_f32_16x16x32_bf16 v[164:167], v[132:135], v[156:159], v[164:167]
	v_mfma_f32_16x16x32_bf16 v[108:111], v[124:127], v[172:175], v[108:111]
	v_mfma_f32_16x16x32_bf16 v[104:107], v[132:135], v[172:175], v[104:107]
	v_mfma_f32_16x16x32_bf16 v[92:95], v[124:127], v[180:183], v[92:95]
	v_mfma_f32_16x16x32_bf16 v[88:91], v[132:135], v[180:183], v[88:91]
	v_mfma_f32_16x16x32_bf16 v[76:79], v[124:127], v[208:211], v[76:79]
	v_mfma_f32_16x16x32_bf16 v[72:75], v[132:135], v[208:211], v[72:75]
	v_mfma_f32_16x16x32_bf16 v[116:119], v[136:139], v[152:155], v[116:119]
	v_mfma_f32_16x16x32_bf16 v[112:115], v[144:147], v[152:155], v[112:115]
	v_mfma_f32_16x16x32_bf16 v[100:103], v[136:139], v[160:163], v[100:103]
	v_mfma_f32_16x16x32_bf16 v[96:99], v[144:147], v[160:163], v[96:99]
	v_mfma_f32_16x16x32_bf16 v[84:87], v[136:139], v[176:179], v[84:87]
	v_mfma_f32_16x16x32_bf16 v[80:83], v[144:147], v[176:179], v[80:83]
	v_mfma_f32_16x16x32_bf16 v[68:71], v[136:139], v[184:187], v[68:71]
	v_mfma_f32_16x16x32_bf16 v[64:67], v[144:147], v[184:187], v[64:67]
	v_mfma_f32_16x16x32_bf16 v[116:119], v[140:143], v[156:159], v[116:119]
	v_mfma_f32_16x16x32_bf16 v[112:115], v[148:151], v[156:159], v[112:115]
	v_mfma_f32_16x16x32_bf16 v[100:103], v[140:143], v[172:175], v[100:103]
	v_mfma_f32_16x16x32_bf16 v[96:99], v[148:151], v[172:175], v[96:99]
	v_mfma_f32_16x16x32_bf16 v[84:87], v[140:143], v[180:183], v[84:87]
	v_mfma_f32_16x16x32_bf16 v[80:83], v[148:151], v[180:183], v[80:83]
	v_mfma_f32_16x16x32_bf16 v[68:71], v[140:143], v[208:211], v[68:71]
	v_mfma_f32_16x16x32_bf16 v[64:67], v[148:151], v[208:211], v[64:67]
	s_barrier
	s_add_i32 s33, s33, s89
	s_mov_b64 s[100:101], vcc
	s_mov_b32 m0, s33
	ds_read_b128 v[152:155], v248 offset:16384
	ds_read_b128 v[156:159], v248 offset:17408
	ds_read_b128 v[160:163], v248 offset:18432
	ds_read_b128 v[172:175], v248 offset:19456
	ds_read_b128 v[176:179], v248 offset:20480
	ds_read_b128 v[180:183], v248 offset:21504
	ds_read_b128 v[184:187], v248 offset:22528
	ds_read_b128 v[208:211], v248 offset:23552
	global_load_lds_dwordx4 v188, s[100:101]
	s_add_i32 m0, s33, 0x2000
	s_add_u32 s36, vcc_lo, s92
	s_addc_u32 s37, vcc_hi, 0
	s_add_i32 s3, s3, s89
	global_load_lds_dwordx4 v206, s[100:101]
	s_mov_b32 m0, s3
	s_nop 0
	global_load_lds_dwordx4 v188, s[36:37]
	s_add_i32 m0, s3, 0x2000
	s_nop 0
	global_load_lds_dwordx4 v206, s[36:37]
	s_mov_b32 m0, s94
	s_nop 0
	global_load_lds_dwordx4 v202, s[46:47]
	s_mov_b32 m0, s95
	s_nop 0
	global_load_lds_dwordx4 v204, s[46:47]
	s_waitcnt vmcnt(8)
	s_waitcnt lgkmcnt(0)
	s_barrier
	s_waitcnt lgkmcnt(0)
	v_mfma_f32_16x16x32_bf16 v[60:63], v[120:123], v[152:155], v[60:63]
	v_mfma_f32_16x16x32_bf16 v[56:59], v[128:131], v[152:155], v[56:59]
	v_mfma_f32_16x16x32_bf16 v[44:47], v[120:123], v[160:163], v[44:47]
	v_mfma_f32_16x16x32_bf16 v[40:43], v[128:131], v[160:163], v[40:43]
	v_mfma_f32_16x16x32_bf16 v[28:31], v[120:123], v[176:179], v[28:31]
	v_mfma_f32_16x16x32_bf16 v[24:27], v[128:131], v[176:179], v[24:27]
	v_mfma_f32_16x16x32_bf16 v[12:15], v[120:123], v[184:187], v[12:15]
	v_mfma_f32_16x16x32_bf16 v[8:11], v[128:131], v[184:187], v[8:11]
	v_mfma_f32_16x16x32_bf16 v[60:63], v[124:127], v[156:159], v[60:63]
	v_mfma_f32_16x16x32_bf16 v[56:59], v[132:135], v[156:159], v[56:59]
	v_mfma_f32_16x16x32_bf16 v[44:47], v[124:127], v[172:175], v[44:47]
	v_mfma_f32_16x16x32_bf16 v[40:43], v[132:135], v[172:175], v[40:43]
	v_mfma_f32_16x16x32_bf16 v[28:31], v[124:127], v[180:183], v[28:31]
	v_mfma_f32_16x16x32_bf16 v[24:27], v[132:135], v[180:183], v[24:27]
	v_mfma_f32_16x16x32_bf16 v[12:15], v[124:127], v[208:211], v[12:15]
	v_mfma_f32_16x16x32_bf16 v[8:11], v[132:135], v[208:211], v[8:11]
	v_mfma_f32_16x16x32_bf16 v[52:55], v[136:139], v[152:155], v[52:55]
	v_mfma_f32_16x16x32_bf16 v[48:51], v[144:147], v[152:155], v[48:51]
	v_mfma_f32_16x16x32_bf16 v[36:39], v[136:139], v[160:163], v[36:39]
	v_mfma_f32_16x16x32_bf16 v[32:35], v[144:147], v[160:163], v[32:35]
	v_mfma_f32_16x16x32_bf16 v[20:23], v[136:139], v[176:179], v[20:23]
	v_mfma_f32_16x16x32_bf16 v[16:19], v[144:147], v[176:179], v[16:19]
	v_mfma_f32_16x16x32_bf16 v[4:7], v[136:139], v[184:187], v[4:7]
	v_mfma_f32_16x16x32_bf16 v[0:3], v[144:147], v[184:187], v[0:3]
	v_mfma_f32_16x16x32_bf16 v[52:55], v[140:143], v[156:159], v[52:55]
	v_mfma_f32_16x16x32_bf16 v[48:51], v[148:151], v[156:159], v[48:51]
	v_mfma_f32_16x16x32_bf16 v[36:39], v[140:143], v[172:175], v[36:39]
	v_mfma_f32_16x16x32_bf16 v[32:35], v[148:151], v[172:175], v[32:35]
	v_mfma_f32_16x16x32_bf16 v[20:23], v[140:143], v[180:183], v[20:23]
	v_mfma_f32_16x16x32_bf16 v[16:19], v[148:151], v[180:183], v[16:19]
	v_mfma_f32_16x16x32_bf16 v[4:7], v[140:143], v[208:211], v[4:7]
	v_mfma_f32_16x16x32_bf16 v[0:3], v[148:151], v[208:211], v[0:3]
	s_barrier
	s_add_i32 s3, 0, 0x18000
	s_add_i32 s33, 0, 0x1c000
	ds_read_b128 v[120:123], v212 offset:32768
	ds_read_b128 v[124:127], v212 offset:33792
	ds_read_b128 v[128:131], v212 offset:34816
	ds_read_b128 v[132:135], v212 offset:35840
	ds_read_b128 v[136:139], v212 offset:49152
	ds_read_b128 v[140:143], v212 offset:50176
	ds_read_b128 v[144:147], v212 offset:51200
	ds_read_b128 v[148:151], v212 offset:52224
	s_add_u32 s36, s46, s92
	s_addc_u32 s37, s47, 0
	s_mov_b32 m0, s96
	ds_read_b128 v[152:155], v248 offset:32768
	ds_read_b128 v[156:159], v248 offset:33792
	ds_read_b128 v[160:163], v248 offset:34816
	ds_read_b128 v[172:175], v248 offset:35840
	ds_read_b128 v[176:179], v248 offset:36864
	ds_read_b128 v[180:183], v248 offset:37888
	ds_read_b128 v[184:187], v248 offset:38912
	ds_read_b128 v[208:211], v248 offset:39936
	global_load_lds_dwordx4 v202, s[36:37]
	s_mov_b32 m0, s97
	s_nop 0
	global_load_lds_dwordx4 v204, s[36:37]
	s_waitcnt vmcnt(8)
	s_waitcnt lgkmcnt(0)
	s_barrier
	s_waitcnt lgkmcnt(0)
	v_mfma_f32_16x16x32_bf16 v[168:171], v[120:123], v[152:155], v[168:171]
	v_mfma_f32_16x16x32_bf16 v[164:167], v[128:131], v[152:155], v[164:167]
	v_mfma_f32_16x16x32_bf16 v[108:111], v[120:123], v[160:163], v[108:111]
	v_mfma_f32_16x16x32_bf16 v[104:107], v[128:131], v[160:163], v[104:107]
	v_mfma_f32_16x16x32_bf16 v[92:95], v[120:123], v[176:179], v[92:95]
	v_mfma_f32_16x16x32_bf16 v[88:91], v[128:131], v[176:179], v[88:91]
	v_mfma_f32_16x16x32_bf16 v[76:79], v[120:123], v[184:187], v[76:79]
	v_mfma_f32_16x16x32_bf16 v[72:75], v[128:131], v[184:187], v[72:75]
	v_mfma_f32_16x16x32_bf16 v[168:171], v[124:127], v[156:159], v[168:171]
	v_mfma_f32_16x16x32_bf16 v[164:167], v[132:135], v[156:159], v[164:167]
	v_mfma_f32_16x16x32_bf16 v[108:111], v[124:127], v[172:175], v[108:111]
	v_mfma_f32_16x16x32_bf16 v[104:107], v[132:135], v[172:175], v[104:107]
	v_mfma_f32_16x16x32_bf16 v[92:95], v[124:127], v[180:183], v[92:95]
	v_mfma_f32_16x16x32_bf16 v[88:91], v[132:135], v[180:183], v[88:91]
	v_mfma_f32_16x16x32_bf16 v[76:79], v[124:127], v[208:211], v[76:79]
	v_mfma_f32_16x16x32_bf16 v[72:75], v[132:135], v[208:211], v[72:75]
	v_mfma_f32_16x16x32_bf16 v[116:119], v[136:139], v[152:155], v[116:119]
	v_mfma_f32_16x16x32_bf16 v[112:115], v[144:147], v[152:155], v[112:115]
	v_mfma_f32_16x16x32_bf16 v[100:103], v[136:139], v[160:163], v[100:103]
	v_mfma_f32_16x16x32_bf16 v[96:99], v[144:147], v[160:163], v[96:99]
	v_mfma_f32_16x16x32_bf16 v[84:87], v[136:139], v[176:179], v[84:87]
	v_mfma_f32_16x16x32_bf16 v[80:83], v[144:147], v[176:179], v[80:83]
	v_mfma_f32_16x16x32_bf16 v[68:71], v[136:139], v[184:187], v[68:71]
	v_mfma_f32_16x16x32_bf16 v[64:67], v[144:147], v[184:187], v[64:67]
	v_mfma_f32_16x16x32_bf16 v[116:119], v[140:143], v[156:159], v[116:119]
	v_mfma_f32_16x16x32_bf16 v[112:115], v[148:151], v[156:159], v[112:115]
	v_mfma_f32_16x16x32_bf16 v[100:103], v[140:143], v[172:175], v[100:103]
	v_mfma_f32_16x16x32_bf16 v[96:99], v[148:151], v[172:175], v[96:99]
	v_mfma_f32_16x16x32_bf16 v[84:87], v[140:143], v[180:183], v[84:87]
	v_mfma_f32_16x16x32_bf16 v[80:83], v[148:151], v[180:183], v[80:83]
	v_mfma_f32_16x16x32_bf16 v[68:71], v[140:143], v[208:211], v[68:71]
	v_mfma_f32_16x16x32_bf16 v[64:67], v[148:151], v[208:211], v[64:67]
	s_barrier
	s_add_i32 s3, s3, s89
	s_add_u32 s100, vcc_lo, 0x80
	s_addc_u32 s101, vcc_hi, 0
	s_mov_b32 m0, s3
	ds_read_b128 v[152:155], v248 offset:49152
	ds_read_b128 v[156:159], v248 offset:50176
	ds_read_b128 v[160:163], v248 offset:51200
	ds_read_b128 v[172:175], v248 offset:52224
	ds_read_b128 v[176:179], v248 offset:53248
	ds_read_b128 v[180:183], v248 offset:54272
	ds_read_b128 v[184:187], v248 offset:55296
	ds_read_b128 v[208:211], v248 offset:56320
	global_load_lds_dwordx4 v188, s[100:101]
	s_add_i32 m0, s3, 0x2000
	s_add_i32 s3, s33, s89
	global_load_lds_dwordx4 v206, s[100:101]
	s_add_u32 s36, s100, s92
	s_addc_u32 s37, s101, 0
	s_mov_b32 m0, s3
	s_nop 0
	global_load_lds_dwordx4 v188, s[36:37]
	s_add_i32 m0, s3, 0x2000
	s_nop 0
	global_load_lds_dwordx4 v206, s[36:37]
	s_add_u32 s100, s46, 0x80
	s_addc_u32 s101, s47, 0
	s_mov_b32 m0, s76
	s_nop 0
	global_load_lds_dwordx4 v202, s[100:101]
	s_mov_b32 m0, s77
	s_nop 0
	global_load_lds_dwordx4 v204, s[100:101]
	s_waitcnt vmcnt(8)
	s_waitcnt lgkmcnt(0)
	s_barrier
	s_waitcnt lgkmcnt(0)
	v_mfma_f32_16x16x32_bf16 v[60:63], v[120:123], v[152:155], v[60:63]
	v_mfma_f32_16x16x32_bf16 v[56:59], v[128:131], v[152:155], v[56:59]
	v_mfma_f32_16x16x32_bf16 v[44:47], v[120:123], v[160:163], v[44:47]
	v_mfma_f32_16x16x32_bf16 v[40:43], v[128:131], v[160:163], v[40:43]
	v_mfma_f32_16x16x32_bf16 v[28:31], v[120:123], v[176:179], v[28:31]
	v_mfma_f32_16x16x32_bf16 v[24:27], v[128:131], v[176:179], v[24:27]
	v_mfma_f32_16x16x32_bf16 v[12:15], v[120:123], v[184:187], v[12:15]
	v_mfma_f32_16x16x32_bf16 v[8:11], v[128:131], v[184:187], v[8:11]
	v_mfma_f32_16x16x32_bf16 v[60:63], v[124:127], v[156:159], v[60:63]
	v_mfma_f32_16x16x32_bf16 v[56:59], v[132:135], v[156:159], v[56:59]
	v_mfma_f32_16x16x32_bf16 v[44:47], v[124:127], v[172:175], v[44:47]
	v_mfma_f32_16x16x32_bf16 v[40:43], v[132:135], v[172:175], v[40:43]
	v_mfma_f32_16x16x32_bf16 v[28:31], v[124:127], v[180:183], v[28:31]
	v_mfma_f32_16x16x32_bf16 v[24:27], v[132:135], v[180:183], v[24:27]
	v_mfma_f32_16x16x32_bf16 v[12:15], v[124:127], v[208:211], v[12:15]
	v_mfma_f32_16x16x32_bf16 v[8:11], v[132:135], v[208:211], v[8:11]
	v_mfma_f32_16x16x32_bf16 v[52:55], v[136:139], v[152:155], v[52:55]
	v_mfma_f32_16x16x32_bf16 v[48:51], v[144:147], v[152:155], v[48:51]
	v_mfma_f32_16x16x32_bf16 v[36:39], v[136:139], v[160:163], v[36:39]
	v_mfma_f32_16x16x32_bf16 v[32:35], v[144:147], v[160:163], v[32:35]
	v_mfma_f32_16x16x32_bf16 v[20:23], v[136:139], v[176:179], v[20:23]
	v_mfma_f32_16x16x32_bf16 v[16:19], v[144:147], v[176:179], v[16:19]
	v_mfma_f32_16x16x32_bf16 v[4:7], v[136:139], v[184:187], v[4:7]
	v_mfma_f32_16x16x32_bf16 v[0:3], v[144:147], v[184:187], v[0:3]
	v_mfma_f32_16x16x32_bf16 v[52:55], v[140:143], v[156:159], v[52:55]
	v_mfma_f32_16x16x32_bf16 v[48:51], v[148:151], v[156:159], v[48:51]
	v_mfma_f32_16x16x32_bf16 v[36:39], v[140:143], v[172:175], v[36:39]
	v_mfma_f32_16x16x32_bf16 v[32:35], v[148:151], v[172:175], v[32:35]
	v_mfma_f32_16x16x32_bf16 v[20:23], v[140:143], v[180:183], v[20:23]
	v_mfma_f32_16x16x32_bf16 v[16:19], v[148:151], v[180:183], v[16:19]
	v_mfma_f32_16x16x32_bf16 v[4:7], v[140:143], v[208:211], v[4:7]
	v_mfma_f32_16x16x32_bf16 v[0:3], v[148:151], v[208:211], v[0:3]
	s_barrier
	s_add_i32 s86, s86, 2
	s_cmp_ge_u32 s86, s98
	s_mov_b64 s[36:37], s[38:39]
	s_cbranch_scc0 .LBB0_490

.LBB0_493:
	s_setprio 0
	s_lshl_b32 s17, s17, 8
	v_lshl_or_b32 v208, s16, 8, v236
	v_add_u32_e32 v120, s17, v233
	v_ashrrev_i32_e32 v209, 31, v208
	v_lshlrev_b64 v[224:225], 1, v[208:209]
	v_ashrrev_i32_e32 v121, 31, v120
	v_lshl_add_u64 v[122:123], s[20:21], 0, v[224:225]
	v_lshlrev_b64 v[226:227], 11, v[120:121]
	v_lshl_add_u64 v[124:125], v[122:123], 0, v[226:227]
	global_load_dwordx4 v[250:253], v[124:125], off
	global_load_dwordx4 v[184:187], v[124:125], off offset:256
	v_or_b32_e32 v124, 16, v120
	v_ashrrev_i32_e32 v125, 31, v124
	v_lshlrev_b64 v[222:223], 11, v[124:125]
	v_lshl_add_u64 v[124:125], v[122:123], 0, v[222:223]
	global_load_dwordx4 v[180:183], v[124:125], off
	global_load_dwordx4 v[176:179], v[124:125], off offset:256
	v_or_b32_e32 v124, 32, v120
	v_or_b32_e32 v120, 48, v120
	v_ashrrev_i32_e32 v125, 31, v124
	v_ashrrev_i32_e32 v121, 31, v120
	v_lshlrev_b64 v[220:221], 11, v[124:125]
	v_lshlrev_b64 v[218:219], 11, v[120:121]
	s_mov_b64 s[2:3], 0x40000
	v_lshl_add_u64 v[124:125], v[122:123], 0, v[220:221]
	v_lshl_add_u64 v[120:121], v[122:123], 0, v[218:219]
	v_lshl_add_u64 v[216:217], v[226:227], 0, s[2:3]
	s_mov_b64 s[30:31], 0x48000
	global_load_dwordx4 v[172:175], v[124:125], off
	global_load_dwordx4 v[160:163], v[124:125], off offset:256
	global_load_dwordx4 v[156:159], v[120:121], off
	global_load_dwordx4 v[152:155], v[120:121], off offset:256
	v_lshl_add_u64 v[120:121], v[122:123], 0, v[216:217]
	v_lshl_add_u64 v[214:215], v[226:227], 0, s[30:31]
	s_mov_b64 s[30:31], 0x50000
	global_load_dwordx4 v[148:151], v[120:121], off
	global_load_dwordx4 v[140:143], v[120:121], off offset:256
	v_lshl_add_u64 v[120:121], v[122:123], 0, v[214:215]
	v_lshl_add_u64 v[212:213], v[226:227], 0, s[30:31]
	s_mov_b64 s[30:31], 0x58000
	global_load_dwordx4 v[144:147], v[120:121], off
	global_load_dwordx4 v[136:139], v[120:121], off offset:256
	v_lshl_add_u64 v[120:121], v[122:123], 0, v[212:213]
	v_lshl_add_u64 v[210:211], v[226:227], 0, s[30:31]
	global_load_dwordx4 v[132:135], v[120:121], off
	global_load_dwordx4 v[128:131], v[120:121], off offset:256
	v_lshl_add_u64 v[120:121], v[122:123], 0, v[210:211]
	global_load_dwordx4 v[124:127], v[120:121], off
	s_nop 0
	global_load_dwordx4 v[120:123], v[120:121], off offset:256
	s_waitcnt vmcnt(0) lgkmcnt(0)
	v_lshlrev_b32_e32 v254, 16, v250
	v_fmac_f32_e32 v254, v235, v168
	v_and_b32_e32 v168, 0xffff0000, v250
	v_fmac_f32_e32 v168, v235, v169
	v_lshlrev_b32_e32 v169, 16, v251
	v_fmac_f32_e32 v169, v235, v170
	v_and_b32_e32 v170, 0xffff0000, v251
	v_fmac_f32_e32 v170, v235, v171
	v_cvt_pk_bf16_f32 v168, v254, v168
	v_cvt_pk_bf16_f32 v169, v169, v170
	v_lshlrev_b32_e32 v170, 16, v252
	v_fmac_f32_e32 v170, v235, v164
	v_and_b32_e32 v164, 0xffff0000, v252
	v_fmac_f32_e32 v164, v235, v165
	v_cvt_pk_bf16_f32 v170, v170, v164
	v_lshlrev_b32_e32 v164, 16, v253
	v_and_b32_e32 v165, 0xffff0000, v253
	v_fmac_f32_e32 v164, v235, v166
	v_fmac_f32_e32 v165, v235, v167
	v_cvt_pk_bf16_f32 v171, v164, v165
	v_lshl_add_u64 v[164:165], s[20:21], 0, v[226:227]
	v_lshl_add_u64 v[164:165], v[164:165], 0, v[224:225]
	v_and_b32_e32 v167, 0xffff0000, v168
	global_store_dwordx4 v[164:165], v[168:171], off
	v_lshlrev_b32_e32 v166, 16, v168
	v_mul_f32_e32 v167, v167, v167
	v_and_b32_e32 v168, 0xffff0000, v169
	v_fmac_f32_e32 v167, v166, v166
	v_lshlrev_b32_e32 v166, 16, v169
	v_mul_f32_e32 v168, v168, v168
	v_fmac_f32_e32 v168, v166, v166
	v_add_f32_e32 v166, v167, v168
	v_and_b32_e32 v168, 0xffff0000, v170
	v_lshlrev_b32_e32 v167, 16, v170
	v_mul_f32_e32 v168, v168, v168
	v_fmac_f32_e32 v168, v167, v167
	v_add_f32_e32 v166, v166, v168
	v_and_b32_e32 v168, 0xffff0000, v171
	v_lshlrev_b32_e32 v167, 16, v171
	v_mul_f32_e32 v168, v168, v168
	v_fmac_f32_e32 v168, v167, v167
	v_lshlrev_b32_e32 v167, 16, v184
	v_fmac_f32_e32 v167, v235, v116
	v_and_b32_e32 v116, 0xffff0000, v184
	v_fmac_f32_e32 v116, v235, v117
	v_lshlrev_b32_e32 v117, 16, v185
	v_fmac_f32_e32 v117, v235, v118
	v_and_b32_e32 v118, 0xffff0000, v185
	v_fmac_f32_e32 v118, v235, v119
	v_cvt_pk_bf16_f32 v116, v167, v116
	v_cvt_pk_bf16_f32 v117, v117, v118
	v_lshlrev_b32_e32 v118, 16, v186
	v_fmac_f32_e32 v118, v235, v112
	v_and_b32_e32 v112, 0xffff0000, v186
	v_fmac_f32_e32 v112, v235, v113
	v_and_b32_e32 v113, 0xffff0000, v187
	v_cvt_pk_bf16_f32 v118, v118, v112
	v_lshlrev_b32_e32 v112, 16, v187
	v_fmac_f32_e32 v113, v235, v115
	v_fmac_f32_e32 v112, v235, v114
	v_cvt_pk_bf16_f32 v119, v112, v113
	v_and_b32_e32 v113, 0xffff0000, v116
	v_lshlrev_b32_e32 v112, 16, v116
	v_mul_f32_e32 v113, v113, v113
	v_and_b32_e32 v114, 0xffff0000, v117
	v_fmac_f32_e32 v113, v112, v112
	v_lshlrev_b32_e32 v112, 16, v117
	v_mul_f32_e32 v114, v114, v114
	v_fmac_f32_e32 v114, v112, v112
	v_add_f32_e32 v112, v113, v114
	v_and_b32_e32 v114, 0xffff0000, v118
	v_lshlrev_b32_e32 v113, 16, v118
	v_mul_f32_e32 v114, v114, v114
	v_fmac_f32_e32 v114, v113, v113
	v_add_f32_e32 v112, v112, v114
	v_and_b32_e32 v114, 0xffff0000, v119
	v_lshlrev_b32_e32 v113, 16, v119
	v_mul_f32_e32 v114, v114, v114
	v_fmac_f32_e32 v114, v113, v113
	v_add_f32_e32 v166, v166, v168
	v_add_f32_e32 v112, v112, v114
	v_add_f32_e32 v112, v166, v112
	ds_bpermute_b32 v113, v237, v112
	global_store_dwordx4 v[164:165], v[116:119], off offset:256
	s_waitcnt lgkmcnt(0)
	v_add_f32_e32 v112, v112, v113
	ds_bpermute_b32 v113, v238, v112
	s_and_saveexec_b64 s[30:31], s[4:5]
	s_cbranch_execz .LBB0_495
	s_waitcnt lgkmcnt(0)
	v_add_f32_e32 v112, v112, v113
	ds_write_b32 v240, v112

.LBB0_527:
	s_ashr_i32 s19, s18, 31
	s_lshl_b64 s[20:21], s[18:19], 19
	s_add_u32 s20, s50, s20
	s_addc_u32 s21, s51, s21
	s_and_b64 s[22:23], s[4:5], exec
	s_cselect_b32 s19, s21, s29
	s_cselect_b32 s25, s20, s28
	s_ashr_i32 s17, s16, 31
	s_lshl_b64 s[22:23], s[16:17], 19
	s_add_u32 s22, s46, s22
	s_addc_u32 s23, s47, s23
	s_and_b64 s[30:31], s[4:5], exec
	s_cselect_b32 s0, s23, s27
	s_cselect_b32 s17, s22, s26
	s_mov_b64 s[30:31], 0
	s_mov_b32 s43, -2
	v_add_u32_e32 v186, 0x10000, v141
	s_and_b64 vcc, exec, s[14:15]
	s_cbranch_vccnz .Lprio_sw
	s_setprio 1
.Lprio_sw:
	s_add_u32 s34, s30, 0x100
	s_addc_u32 s35, s31, 0
	s_add_u32 s38, s30, 0xfffff900
	s_addc_u32 s39, s31, -1
	s_cmp_gt_u32 s34, 0x7ff
	s_cselect_b32 s34, s38, s34
	s_cselect_b32 s35, s39, s35
	s_add_u32 s36, s28, s34
	s_addc_u32 s37, s29, s35
	s_add_u32 s76, s26, s34
	s_addc_u32 s77, s27, s35
	s_add_i32 s86, 0, 0x10000
	s_cmp_eq_u32 s43, 12
	s_cselect_b32 s39, s19, s37
	s_cselect_b32 s38, s25, s36
	s_cselect_b32 s37, s0, s77
	s_cselect_b32 s36, s17, s76
	s_add_i32 s76, 0, 0x14000
	ds_read_b128 v[96:99], v186
	ds_read_b128 v[150:153], v186 offset:1024
	ds_read_b128 v[154:157], v186 offset:2048
	ds_read_b128 v[158:161], v186 offset:3072
	ds_read_b128 v[162:165], v186 offset:16384
	ds_read_b128 v[166:169], v186 offset:17408
	ds_read_b128 v[170:173], v186 offset:18432
	ds_read_b128 v[174:177], v186 offset:19456
	s_add_u32 s30, s28, s30
	s_addc_u32 s31, s29, s31
	s_add_u32 s30, s30, 0x40080
	s_addc_u32 s31, s31, 0
	s_add_i32 m0, s60, 0xc000
	ds_read_b128 v[178:181], v149
	ds_read_b128 v[182:185], v149 offset:1024
	ds_read_b128 v[202:205], v149 offset:2048
	ds_read_b128 v[206:209], v149 offset:3072
	ds_read_b128 v[210:213], v149 offset:4096
	ds_read_b128 v[214:217], v149 offset:5120
	ds_read_b128 v[218:221], v149 offset:6144
	ds_read_b128 v[222:225], v149 offset:7168
	global_load_lds_dwordx4 v136, s[30:31]
	s_add_i32 m0, s60, 0xe000
	s_nop 0
	global_load_lds_dwordx4 v134, s[30:31]
	s_waitcnt vmcnt(8)
	s_waitcnt lgkmcnt(0)
	s_barrier
	s_waitcnt lgkmcnt(0)
	v_mfma_f32_16x16x32_bf16 v[128:131], v[96:99], v[178:181], 0
	v_mfma_f32_16x16x32_bf16 v[120:123], v[154:157], v[178:181], 0
	v_mfma_f32_16x16x32_bf16 v[112:115], v[96:99], v[202:205], 0
	v_mfma_f32_16x16x32_bf16 v[104:107], v[154:157], v[202:205], 0
	v_mfma_f32_16x16x32_bf16 v[92:95], v[96:99], v[210:213], 0
	v_mfma_f32_16x16x32_bf16 v[84:87], v[154:157], v[210:213], 0
	v_mfma_f32_16x16x32_bf16 v[76:79], v[96:99], v[218:221], 0
	v_mfma_f32_16x16x32_bf16 v[68:71], v[154:157], v[218:221], 0
	v_mfma_f32_16x16x32_bf16 v[128:131], v[150:153], v[182:185], v[128:131]
	v_mfma_f32_16x16x32_bf16 v[120:123], v[158:161], v[182:185], v[120:123]
	v_mfma_f32_16x16x32_bf16 v[112:115], v[150:153], v[206:209], v[112:115]
	v_mfma_f32_16x16x32_bf16 v[104:107], v[158:161], v[206:209], v[104:107]
	v_mfma_f32_16x16x32_bf16 v[92:95], v[150:153], v[214:217], v[92:95]
	v_mfma_f32_16x16x32_bf16 v[84:87], v[158:161], v[214:217], v[84:87]
	v_mfma_f32_16x16x32_bf16 v[76:79], v[150:153], v[222:225], v[76:79]
	v_mfma_f32_16x16x32_bf16 v[68:71], v[158:161], v[222:225], v[68:71]
	v_mfma_f32_16x16x32_bf16 v[124:127], v[162:165], v[178:181], 0
	v_mfma_f32_16x16x32_bf16 v[116:119], v[170:173], v[178:181], 0
	v_mfma_f32_16x16x32_bf16 v[108:111], v[162:165], v[202:205], 0
	v_mfma_f32_16x16x32_bf16 v[100:103], v[170:173], v[202:205], 0
	v_mfma_f32_16x16x32_bf16 v[88:91], v[162:165], v[210:213], 0
	v_mfma_f32_16x16x32_bf16 v[80:83], v[170:173], v[210:213], 0
	v_mfma_f32_16x16x32_bf16 v[72:75], v[162:165], v[218:221], 0
	v_mfma_f32_16x16x32_bf16 v[64:67], v[170:173], v[218:221], 0
	v_mfma_f32_16x16x32_bf16 v[124:127], v[166:169], v[182:185], v[124:127]
	v_mfma_f32_16x16x32_bf16 v[116:119], v[174:177], v[182:185], v[116:119]
	v_mfma_f32_16x16x32_bf16 v[108:111], v[166:169], v[206:209], v[108:111]
	v_mfma_f32_16x16x32_bf16 v[100:103], v[174:177], v[206:209], v[100:103]
	v_mfma_f32_16x16x32_bf16 v[88:91], v[166:169], v[214:217], v[88:91]
	v_mfma_f32_16x16x32_bf16 v[80:83], v[174:177], v[214:217], v[80:83]
	v_mfma_f32_16x16x32_bf16 v[72:75], v[166:169], v[222:225], v[72:75]
	v_mfma_f32_16x16x32_bf16 v[64:67], v[174:177], v[222:225], v[64:67]
	s_barrier
	s_add_i32 s30, s86, s56
	s_mov_b32 m0, s30
	ds_read_b128 v[178:181], v149 offset:16384
	ds_read_b128 v[182:185], v149 offset:17408
	ds_read_b128 v[202:205], v149 offset:18432
	ds_read_b128 v[206:209], v149 offset:19456
	ds_read_b128 v[210:213], v149 offset:20480
	ds_read_b128 v[214:217], v149 offset:21504
	ds_read_b128 v[218:221], v149 offset:22528
	ds_read_b128 v[222:225], v149 offset:23552
	global_load_lds_dwordx4 v188, s[36:37]
	s_add_i32 m0, s30, 0x2000
	s_add_u32 s30, s36, 0x40000
	s_addc_u32 s31, s37, 0
	s_add_i32 s76, s76, s56
	global_load_lds_dwordx4 v132, s[36:37]
	s_mov_b32 m0, s76
	s_nop 0
	global_load_lds_dwordx4 v188, s[30:31]
	s_add_i32 m0, s76, 0x2000
	s_nop 0
	global_load_lds_dwordx4 v132, s[30:31]
	s_mov_b32 m0, s60
	s_nop 0
	global_load_lds_dwordx4 v136, s[38:39]
	s_mov_b32 m0, s71
	s_nop 0
	global_load_lds_dwordx4 v134, s[38:39]
	s_waitcnt vmcnt(8)
	s_waitcnt lgkmcnt(0)
	s_barrier
	s_waitcnt lgkmcnt(0)
	v_mfma_f32_16x16x32_bf16 v[60:63], v[96:99], v[178:181], 0
	v_mfma_f32_16x16x32_bf16 v[52:55], v[154:157], v[178:181], 0
	v_mfma_f32_16x16x32_bf16 v[44:47], v[96:99], v[202:205], 0
	v_mfma_f32_16x16x32_bf16 v[36:39], v[154:157], v[202:205], 0
	v_mfma_f32_16x16x32_bf16 v[28:31], v[96:99], v[210:213], 0
	v_mfma_f32_16x16x32_bf16 v[20:23], v[154:157], v[210:213], 0
	v_mfma_f32_16x16x32_bf16 v[12:15], v[96:99], v[218:221], 0
	v_mfma_f32_16x16x32_bf16 v[4:7], v[154:157], v[218:221], 0
	v_mfma_f32_16x16x32_bf16 v[60:63], v[150:153], v[182:185], v[60:63]
	v_mfma_f32_16x16x32_bf16 v[52:55], v[158:161], v[182:185], v[52:55]
	v_mfma_f32_16x16x32_bf16 v[44:47], v[150:153], v[206:209], v[44:47]
	v_mfma_f32_16x16x32_bf16 v[36:39], v[158:161], v[206:209], v[36:39]
	v_mfma_f32_16x16x32_bf16 v[28:31], v[150:153], v[214:217], v[28:31]
	v_mfma_f32_16x16x32_bf16 v[20:23], v[158:161], v[214:217], v[20:23]
	v_mfma_f32_16x16x32_bf16 v[12:15], v[150:153], v[222:225], v[12:15]
	v_mfma_f32_16x16x32_bf16 v[4:7], v[158:161], v[222:225], v[4:7]
	v_mfma_f32_16x16x32_bf16 v[56:59], v[162:165], v[178:181], 0
	v_mfma_f32_16x16x32_bf16 v[48:51], v[170:173], v[178:181], 0
	v_mfma_f32_16x16x32_bf16 v[40:43], v[162:165], v[202:205], 0
	v_mfma_f32_16x16x32_bf16 v[32:35], v[170:173], v[202:205], 0
	v_mfma_f32_16x16x32_bf16 v[24:27], v[162:165], v[210:213], 0
	v_mfma_f32_16x16x32_bf16 v[16:19], v[170:173], v[210:213], 0
	v_mfma_f32_16x16x32_bf16 v[8:11], v[162:165], v[218:221], 0
	v_mfma_f32_16x16x32_bf16 v[0:3], v[170:173], v[218:221], 0
	v_mfma_f32_16x16x32_bf16 v[56:59], v[166:169], v[182:185], v[56:59]
	v_mfma_f32_16x16x32_bf16 v[48:51], v[174:177], v[182:185], v[48:51]
	v_mfma_f32_16x16x32_bf16 v[40:43], v[166:169], v[206:209], v[40:43]
	v_mfma_f32_16x16x32_bf16 v[32:35], v[174:177], v[206:209], v[32:35]
	v_mfma_f32_16x16x32_bf16 v[24:27], v[166:169], v[214:217], v[24:27]
	v_mfma_f32_16x16x32_bf16 v[16:19], v[174:177], v[214:217], v[16:19]
	v_mfma_f32_16x16x32_bf16 v[8:11], v[166:169], v[222:225], v[8:11]
	v_mfma_f32_16x16x32_bf16 v[0:3], v[174:177], v[222:225], v[0:3]
	s_barrier
	s_add_i32 s76, 0, 0x18000
	s_add_i32 s77, 0, 0x1c000
	ds_read_b128 v[96:99], v186 offset:32768
	ds_read_b128 v[150:153], v186 offset:33792
	ds_read_b128 v[154:157], v186 offset:34816
	ds_read_b128 v[158:161], v186 offset:35840
	ds_read_b128 v[162:165], v186 offset:49152
	ds_read_b128 v[166:169], v186 offset:50176
	ds_read_b128 v[170:173], v186 offset:51200
	ds_read_b128 v[174:177], v186 offset:52224
	s_add_u32 s30, s38, 0x40000
	s_addc_u32 s31, s39, 0
	s_mov_b32 m0, s87
	ds_read_b128 v[178:181], v149 offset:32768
	ds_read_b128 v[182:185], v149 offset:33792
	ds_read_b128 v[202:205], v149 offset:34816
	ds_read_b128 v[206:209], v149 offset:35840
	ds_read_b128 v[210:213], v149 offset:36864
	ds_read_b128 v[214:217], v149 offset:37888
	ds_read_b128 v[218:221], v149 offset:38912
	ds_read_b128 v[222:225], v149 offset:39936
	global_load_lds_dwordx4 v136, s[30:31]
	s_mov_b32 m0, s89
	s_nop 0
	global_load_lds_dwordx4 v134, s[30:31]
	s_waitcnt vmcnt(8)
	s_waitcnt lgkmcnt(0)
	s_barrier
	s_waitcnt lgkmcnt(0)
	v_mfma_f32_16x16x32_bf16 v[128:131], v[96:99], v[178:181], v[128:131]
	v_mfma_f32_16x16x32_bf16 v[120:123], v[154:157], v[178:181], v[120:123]
	v_mfma_f32_16x16x32_bf16 v[112:115], v[96:99], v[202:205], v[112:115]
	v_mfma_f32_16x16x32_bf16 v[104:107], v[154:157], v[202:205], v[104:107]
	v_mfma_f32_16x16x32_bf16 v[92:95], v[96:99], v[210:213], v[92:95]
	v_mfma_f32_16x16x32_bf16 v[84:87], v[154:157], v[210:213], v[84:87]
	v_mfma_f32_16x16x32_bf16 v[76:79], v[96:99], v[218:221], v[76:79]
	v_mfma_f32_16x16x32_bf16 v[68:71], v[154:157], v[218:221], v[68:71]
	v_mfma_f32_16x16x32_bf16 v[128:131], v[150:153], v[182:185], v[128:131]
	v_mfma_f32_16x16x32_bf16 v[120:123], v[158:161], v[182:185], v[120:123]
	v_mfma_f32_16x16x32_bf16 v[112:115], v[150:153], v[206:209], v[112:115]
	v_mfma_f32_16x16x32_bf16 v[104:107], v[158:161], v[206:209], v[104:107]
	v_mfma_f32_16x16x32_bf16 v[92:95], v[150:153], v[214:217], v[92:95]
	v_mfma_f32_16x16x32_bf16 v[84:87], v[158:161], v[214:217], v[84:87]
	v_mfma_f32_16x16x32_bf16 v[76:79], v[150:153], v[222:225], v[76:79]
	v_mfma_f32_16x16x32_bf16 v[68:71], v[158:161], v[222:225], v[68:71]
	v_mfma_f32_16x16x32_bf16 v[124:127], v[162:165], v[178:181], v[124:127]
	v_mfma_f32_16x16x32_bf16 v[116:119], v[170:173], v[178:181], v[116:119]
	v_mfma_f32_16x16x32_bf16 v[108:111], v[162:165], v[202:205], v[108:111]
	v_mfma_f32_16x16x32_bf16 v[100:103], v[170:173], v[202:205], v[100:103]
	v_mfma_f32_16x16x32_bf16 v[88:91], v[162:165], v[210:213], v[88:91]
	v_mfma_f32_16x16x32_bf16 v[80:83], v[170:173], v[210:213], v[80:83]
	v_mfma_f32_16x16x32_bf16 v[72:75], v[162:165], v[218:221], v[72:75]
	v_mfma_f32_16x16x32_bf16 v[64:67], v[170:173], v[218:221], v[64:67]
	v_mfma_f32_16x16x32_bf16 v[124:127], v[166:169], v[182:185], v[124:127]
	v_mfma_f32_16x16x32_bf16 v[116:119], v[174:177], v[182:185], v[116:119]
	v_mfma_f32_16x16x32_bf16 v[108:111], v[166:169], v[206:209], v[108:111]
	v_mfma_f32_16x16x32_bf16 v[100:103], v[174:177], v[206:209], v[100:103]
	v_mfma_f32_16x16x32_bf16 v[88:91], v[166:169], v[214:217], v[88:91]
	v_mfma_f32_16x16x32_bf16 v[80:83], v[174:177], v[214:217], v[80:83]
	v_mfma_f32_16x16x32_bf16 v[72:75], v[166:169], v[222:225], v[72:75]
	v_mfma_f32_16x16x32_bf16 v[64:67], v[174:177], v[222:225], v[64:67]
	s_barrier
	s_add_i32 s30, s76, s56
	s_add_u32 s100, s36, 0x80
	s_addc_u32 s101, s37, 0
	s_mov_b32 m0, s30
	ds_read_b128 v[178:181], v149 offset:49152
	ds_read_b128 v[182:185], v149 offset:50176
	ds_read_b128 v[202:205], v149 offset:51200
	ds_read_b128 v[206:209], v149 offset:52224
	ds_read_b128 v[210:213], v149 offset:53248
	ds_read_b128 v[214:217], v149 offset:54272
	ds_read_b128 v[218:221], v149 offset:55296
	ds_read_b128 v[222:225], v149 offset:56320
	global_load_lds_dwordx4 v188, s[100:101]
	s_add_i32 m0, s30, 0x2000
	s_add_u32 s30, s36, 0x40080
	s_addc_u32 s31, s37, 0
	s_add_i32 s36, s77, s56
	global_load_lds_dwordx4 v132, s[100:101]
	s_mov_b32 m0, s36
	s_nop 0
	global_load_lds_dwordx4 v188, s[30:31]
	s_add_i32 m0, s36, 0x2000
	s_nop 0
	global_load_lds_dwordx4 v132, s[30:31]
	s_add_u32 s100, s38, 0x80
	s_addc_u32 s101, s39, 0
	s_mov_b32 m0, s90
	s_nop 0
	global_load_lds_dwordx4 v136, s[100:101]
	s_mov_b32 m0, s91
	s_nop 0
	global_load_lds_dwordx4 v134, s[100:101]
	s_waitcnt vmcnt(8)
	s_waitcnt lgkmcnt(0)
	s_barrier
	s_waitcnt lgkmcnt(0)
	v_mfma_f32_16x16x32_bf16 v[60:63], v[96:99], v[178:181], v[60:63]
	v_mfma_f32_16x16x32_bf16 v[52:55], v[154:157], v[178:181], v[52:55]
	v_mfma_f32_16x16x32_bf16 v[44:47], v[96:99], v[202:205], v[44:47]
	v_mfma_f32_16x16x32_bf16 v[36:39], v[154:157], v[202:205], v[36:39]
	v_mfma_f32_16x16x32_bf16 v[28:31], v[96:99], v[210:213], v[28:31]
	v_mfma_f32_16x16x32_bf16 v[20:23], v[154:157], v[210:213], v[20:23]
	v_mfma_f32_16x16x32_bf16 v[12:15], v[96:99], v[218:221], v[12:15]
	v_mfma_f32_16x16x32_bf16 v[4:7], v[154:157], v[218:221], v[4:7]
	v_mfma_f32_16x16x32_bf16 v[60:63], v[150:153], v[182:185], v[60:63]
	v_mfma_f32_16x16x32_bf16 v[52:55], v[158:161], v[182:185], v[52:55]
	v_mfma_f32_16x16x32_bf16 v[44:47], v[150:153], v[206:209], v[44:47]
	v_mfma_f32_16x16x32_bf16 v[36:39], v[158:161], v[206:209], v[36:39]
	v_mfma_f32_16x16x32_bf16 v[28:31], v[150:153], v[214:217], v[28:31]
	v_mfma_f32_16x16x32_bf16 v[20:23], v[158:161], v[214:217], v[20:23]
	v_mfma_f32_16x16x32_bf16 v[12:15], v[150:153], v[222:225], v[12:15]
	v_mfma_f32_16x16x32_bf16 v[4:7], v[158:161], v[222:225], v[4:7]
	v_mfma_f32_16x16x32_bf16 v[56:59], v[162:165], v[178:181], v[56:59]
	v_mfma_f32_16x16x32_bf16 v[48:51], v[170:173], v[178:181], v[48:51]
	v_mfma_f32_16x16x32_bf16 v[40:43], v[162:165], v[202:205], v[40:43]
	v_mfma_f32_16x16x32_bf16 v[32:35], v[170:173], v[202:205], v[32:35]
	v_mfma_f32_16x16x32_bf16 v[24:27], v[162:165], v[210:213], v[24:27]
	v_mfma_f32_16x16x32_bf16 v[16:19], v[170:173], v[210:213], v[16:19]
	v_mfma_f32_16x16x32_bf16 v[8:11], v[162:165], v[218:221], v[8:11]
	v_mfma_f32_16x16x32_bf16 v[0:3], v[170:173], v[218:221], v[0:3]
	v_mfma_f32_16x16x32_bf16 v[56:59], v[166:169], v[182:185], v[56:59]
	v_mfma_f32_16x16x32_bf16 v[48:51], v[174:177], v[182:185], v[48:51]
	v_mfma_f32_16x16x32_bf16 v[40:43], v[166:169], v[206:209], v[40:43]
	v_mfma_f32_16x16x32_bf16 v[32:35], v[174:177], v[206:209], v[32:35]
	v_mfma_f32_16x16x32_bf16 v[24:27], v[166:169], v[214:217], v[24:27]
	v_mfma_f32_16x16x32_bf16 v[16:19], v[174:177], v[214:217], v[16:19]
	v_mfma_f32_16x16x32_bf16 v[8:11], v[166:169], v[222:225], v[8:11]
	v_mfma_f32_16x16x32_bf16 v[0:3], v[174:177], v[222:225], v[0:3]
	s_barrier
	s_add_i32 s43, s43, 2
	s_cmp_gt_u32 s43, 13
	s_mov_b64 s[30:31], s[34:35]
	s_cbranch_scc1 .Lpeel_exit_swiglu
.LBB0_528:
	s_add_u32 s34, s30, 0x100
	s_addc_u32 s35, s31, 0
	s_add_u32 s38, s30, 0xfffff900
	s_addc_u32 s39, s31, -1
	s_cmp_gt_u32 s34, 0x7ff
	s_cselect_b32 s34, s38, s34
	s_cselect_b32 s35, s39, s35
	s_add_u32 s36, s28, s34
	s_addc_u32 s37, s29, s35
	s_add_u32 s76, s26, s34
	s_addc_u32 s77, s27, s35
	s_add_i32 s86, 0, 0x10000
	s_cmp_eq_u32 s43, 12
	s_cselect_b32 s39, s19, s37
	s_cselect_b32 s38, s25, s36
	s_cselect_b32 s37, s0, s77
	s_cselect_b32 s36, s17, s76
	s_add_i32 s76, 0, 0x14000
	ds_read_b128 v[96:99], v186
	ds_read_b128 v[150:153], v186 offset:1024
	ds_read_b128 v[154:157], v186 offset:2048
	ds_read_b128 v[158:161], v186 offset:3072
	ds_read_b128 v[162:165], v186 offset:16384
	ds_read_b128 v[166:169], v186 offset:17408
	ds_read_b128 v[170:173], v186 offset:18432
	ds_read_b128 v[174:177], v186 offset:19456
	s_add_u32 s30, s28, s30
	s_addc_u32 s31, s29, s31
	s_add_u32 s30, s30, 0x40080
	s_addc_u32 s31, s31, 0
	s_add_i32 m0, s60, 0xc000
	ds_read_b128 v[178:181], v149
	ds_read_b128 v[182:185], v149 offset:1024
	ds_read_b128 v[202:205], v149 offset:2048
	ds_read_b128 v[206:209], v149 offset:3072
	ds_read_b128 v[210:213], v149 offset:4096
	ds_read_b128 v[214:217], v149 offset:5120
	ds_read_b128 v[218:221], v149 offset:6144
	ds_read_b128 v[222:225], v149 offset:7168
	global_load_lds_dwordx4 v136, s[30:31]
	s_add_i32 m0, s60, 0xe000
	s_nop 0
	global_load_lds_dwordx4 v134, s[30:31]
	s_waitcnt vmcnt(8)
	s_waitcnt lgkmcnt(0)
	s_barrier
	s_waitcnt lgkmcnt(0)
	v_mfma_f32_16x16x32_bf16 v[128:131], v[96:99], v[178:181], v[128:131]
	v_mfma_f32_16x16x32_bf16 v[120:123], v[154:157], v[178:181], v[120:123]
	v_mfma_f32_16x16x32_bf16 v[112:115], v[96:99], v[202:205], v[112:115]
	v_mfma_f32_16x16x32_bf16 v[104:107], v[154:157], v[202:205], v[104:107]
	v_mfma_f32_16x16x32_bf16 v[92:95], v[96:99], v[210:213], v[92:95]
	v_mfma_f32_16x16x32_bf16 v[84:87], v[154:157], v[210:213], v[84:87]
	v_mfma_f32_16x16x32_bf16 v[76:79], v[96:99], v[218:221], v[76:79]
	v_mfma_f32_16x16x32_bf16 v[68:71], v[154:157], v[218:221], v[68:71]
	v_mfma_f32_16x16x32_bf16 v[128:131], v[150:153], v[182:185], v[128:131]
	v_mfma_f32_16x16x32_bf16 v[120:123], v[158:161], v[182:185], v[120:123]
	v_mfma_f32_16x16x32_bf16 v[112:115], v[150:153], v[206:209], v[112:115]
	v_mfma_f32_16x16x32_bf16 v[104:107], v[158:161], v[206:209], v[104:107]
	v_mfma_f32_16x16x32_bf16 v[92:95], v[150:153], v[214:217], v[92:95]
	v_mfma_f32_16x16x32_bf16 v[84:87], v[158:161], v[214:217], v[84:87]
	v_mfma_f32_16x16x32_bf16 v[76:79], v[150:153], v[222:225], v[76:79]
	v_mfma_f32_16x16x32_bf16 v[68:71], v[158:161], v[222:225], v[68:71]
	v_mfma_f32_16x16x32_bf16 v[124:127], v[162:165], v[178:181], v[124:127]
	v_mfma_f32_16x16x32_bf16 v[116:119], v[170:173], v[178:181], v[116:119]
	v_mfma_f32_16x16x32_bf16 v[108:111], v[162:165], v[202:205], v[108:111]
	v_mfma_f32_16x16x32_bf16 v[100:103], v[170:173], v[202:205], v[100:103]
	v_mfma_f32_16x16x32_bf16 v[88:91], v[162:165], v[210:213], v[88:91]
	v_mfma_f32_16x16x32_bf16 v[80:83], v[170:173], v[210:213], v[80:83]
	v_mfma_f32_16x16x32_bf16 v[72:75], v[162:165], v[218:221], v[72:75]
	v_mfma_f32_16x16x32_bf16 v[64:67], v[170:173], v[218:221], v[64:67]
	v_mfma_f32_16x16x32_bf16 v[124:127], v[166:169], v[182:185], v[124:127]
	v_mfma_f32_16x16x32_bf16 v[116:119], v[174:177], v[182:185], v[116:119]
	v_mfma_f32_16x16x32_bf16 v[108:111], v[166:169], v[206:209], v[108:111]
	v_mfma_f32_16x16x32_bf16 v[100:103], v[174:177], v[206:209], v[100:103]
	v_mfma_f32_16x16x32_bf16 v[88:91], v[166:169], v[214:217], v[88:91]
	v_mfma_f32_16x16x32_bf16 v[80:83], v[174:177], v[214:217], v[80:83]
	v_mfma_f32_16x16x32_bf16 v[72:75], v[166:169], v[222:225], v[72:75]
	v_mfma_f32_16x16x32_bf16 v[64:67], v[174:177], v[222:225], v[64:67]
	s_barrier
	s_add_i32 s30, s86, s56
	s_mov_b32 m0, s30
	ds_read_b128 v[178:181], v149 offset:16384
	ds_read_b128 v[182:185], v149 offset:17408
	ds_read_b128 v[202:205], v149 offset:18432
	ds_read_b128 v[206:209], v149 offset:19456
	ds_read_b128 v[210:213], v149 offset:20480
	ds_read_b128 v[214:217], v149 offset:21504
	ds_read_b128 v[218:221], v149 offset:22528
	ds_read_b128 v[222:225], v149 offset:23552
	global_load_lds_dwordx4 v188, s[36:37]
	s_add_i32 m0, s30, 0x2000
	s_add_u32 s30, s36, 0x40000
	s_addc_u32 s31, s37, 0
	s_add_i32 s76, s76, s56
	global_load_lds_dwordx4 v132, s[36:37]
	s_mov_b32 m0, s76
	s_nop 0
	global_load_lds_dwordx4 v188, s[30:31]
	s_add_i32 m0, s76, 0x2000
	s_nop 0
	global_load_lds_dwordx4 v132, s[30:31]
	s_mov_b32 m0, s60
	s_nop 0
	global_load_lds_dwordx4 v136, s[38:39]
	s_mov_b32 m0, s71
	s_nop 0
	global_load_lds_dwordx4 v134, s[38:39]
	s_waitcnt vmcnt(8)
	s_waitcnt lgkmcnt(0)
	s_barrier
	s_waitcnt lgkmcnt(0)
	v_mfma_f32_16x16x32_bf16 v[60:63], v[96:99], v[178:181], v[60:63]
	v_mfma_f32_16x16x32_bf16 v[52:55], v[154:157], v[178:181], v[52:55]
	v_mfma_f32_16x16x32_bf16 v[44:47], v[96:99], v[202:205], v[44:47]
	v_mfma_f32_16x16x32_bf16 v[36:39], v[154:157], v[202:205], v[36:39]
	v_mfma_f32_16x16x32_bf16 v[28:31], v[96:99], v[210:213], v[28:31]
	v_mfma_f32_16x16x32_bf16 v[20:23], v[154:157], v[210:213], v[20:23]
	v_mfma_f32_16x16x32_bf16 v[12:15], v[96:99], v[218:221], v[12:15]
	v_mfma_f32_16x16x32_bf16 v[4:7], v[154:157], v[218:221], v[4:7]
	v_mfma_f32_16x16x32_bf16 v[60:63], v[150:153], v[182:185], v[60:63]
	v_mfma_f32_16x16x32_bf16 v[52:55], v[158:161], v[182:185], v[52:55]
	v_mfma_f32_16x16x32_bf16 v[44:47], v[150:153], v[206:209], v[44:47]
	v_mfma_f32_16x16x32_bf16 v[36:39], v[158:161], v[206:209], v[36:39]
	v_mfma_f32_16x16x32_bf16 v[28:31], v[150:153], v[214:217], v[28:31]
	v_mfma_f32_16x16x32_bf16 v[20:23], v[158:161], v[214:217], v[20:23]
	v_mfma_f32_16x16x32_bf16 v[12:15], v[150:153], v[222:225], v[12:15]
	v_mfma_f32_16x16x32_bf16 v[4:7], v[158:161], v[222:225], v[4:7]
	v_mfma_f32_16x16x32_bf16 v[56:59], v[162:165], v[178:181], v[56:59]
	v_mfma_f32_16x16x32_bf16 v[48:51], v[170:173], v[178:181], v[48:51]
	v_mfma_f32_16x16x32_bf16 v[40:43], v[162:165], v[202:205], v[40:43]
	v_mfma_f32_16x16x32_bf16 v[32:35], v[170:173], v[202:205], v[32:35]
	v_mfma_f32_16x16x32_bf16 v[24:27], v[162:165], v[210:213], v[24:27]
	v_mfma_f32_16x16x32_bf16 v[16:19], v[170:173], v[210:213], v[16:19]
	v_mfma_f32_16x16x32_bf16 v[8:11], v[162:165], v[218:221], v[8:11]
	v_mfma_f32_16x16x32_bf16 v[0:3], v[170:173], v[218:221], v[0:3]
	v_mfma_f32_16x16x32_bf16 v[56:59], v[166:169], v[182:185], v[56:59]
	v_mfma_f32_16x16x32_bf16 v[48:51], v[174:177], v[182:185], v[48:51]
	v_mfma_f32_16x16x32_bf16 v[40:43], v[166:169], v[206:209], v[40:43]
	v_mfma_f32_16x16x32_bf16 v[32:35], v[174:177], v[206:209], v[32:35]
	v_mfma_f32_16x16x32_bf16 v[24:27], v[166:169], v[214:217], v[24:27]
	v_mfma_f32_16x16x32_bf16 v[16:19], v[174:177], v[214:217], v[16:19]
	v_mfma_f32_16x16x32_bf16 v[8:11], v[166:169], v[222:225], v[8:11]
	v_mfma_f32_16x16x32_bf16 v[0:3], v[174:177], v[222:225], v[0:3]
	s_barrier
	s_add_i32 s76, 0, 0x18000
	s_add_i32 s77, 0, 0x1c000
	ds_read_b128 v[96:99], v186 offset:32768
	ds_read_b128 v[150:153], v186 offset:33792
	ds_read_b128 v[154:157], v186 offset:34816
	ds_read_b128 v[158:161], v186 offset:35840
	ds_read_b128 v[162:165], v186 offset:49152
	ds_read_b128 v[166:169], v186 offset:50176
	ds_read_b128 v[170:173], v186 offset:51200
	ds_read_b128 v[174:177], v186 offset:52224
	s_add_u32 s30, s38, 0x40000
	s_addc_u32 s31, s39, 0
	s_mov_b32 m0, s87
	ds_read_b128 v[178:181], v149 offset:32768
	ds_read_b128 v[182:185], v149 offset:33792
	ds_read_b128 v[202:205], v149 offset:34816
	ds_read_b128 v[206:209], v149 offset:35840
	ds_read_b128 v[210:213], v149 offset:36864
	ds_read_b128 v[214:217], v149 offset:37888
	ds_read_b128 v[218:221], v149 offset:38912
	ds_read_b128 v[222:225], v149 offset:39936
	global_load_lds_dwordx4 v136, s[30:31]
	s_mov_b32 m0, s89
	s_nop 0
	global_load_lds_dwordx4 v134, s[30:31]
	s_waitcnt vmcnt(8)
	s_waitcnt lgkmcnt(0)
	s_barrier
	s_waitcnt lgkmcnt(0)
	v_mfma_f32_16x16x32_bf16 v[128:131], v[96:99], v[178:181], v[128:131]
	v_mfma_f32_16x16x32_bf16 v[120:123], v[154:157], v[178:181], v[120:123]
	v_mfma_f32_16x16x32_bf16 v[112:115], v[96:99], v[202:205], v[112:115]
	v_mfma_f32_16x16x32_bf16 v[104:107], v[154:157], v[202:205], v[104:107]
	v_mfma_f32_16x16x32_bf16 v[92:95], v[96:99], v[210:213], v[92:95]
	v_mfma_f32_16x16x32_bf16 v[84:87], v[154:157], v[210:213], v[84:87]
	v_mfma_f32_16x16x32_bf16 v[76:79], v[96:99], v[218:221], v[76:79]
	v_mfma_f32_16x16x32_bf16 v[68:71], v[154:157], v[218:221], v[68:71]
	v_mfma_f32_16x16x32_bf16 v[128:131], v[150:153], v[182:185], v[128:131]
	v_mfma_f32_16x16x32_bf16 v[120:123], v[158:161], v[182:185], v[120:123]
	v_mfma_f32_16x16x32_bf16 v[112:115], v[150:153], v[206:209], v[112:115]
	v_mfma_f32_16x16x32_bf16 v[104:107], v[158:161], v[206:209], v[104:107]
	v_mfma_f32_16x16x32_bf16 v[92:95], v[150:153], v[214:217], v[92:95]
	v_mfma_f32_16x16x32_bf16 v[84:87], v[158:161], v[214:217], v[84:87]
	v_mfma_f32_16x16x32_bf16 v[76:79], v[150:153], v[222:225], v[76:79]
	v_mfma_f32_16x16x32_bf16 v[68:71], v[158:161], v[222:225], v[68:71]
	v_mfma_f32_16x16x32_bf16 v[124:127], v[162:165], v[178:181], v[124:127]
	v_mfma_f32_16x16x32_bf16 v[116:119], v[170:173], v[178:181], v[116:119]
	v_mfma_f32_16x16x32_bf16 v[108:111], v[162:165], v[202:205], v[108:111]
	v_mfma_f32_16x16x32_bf16 v[100:103], v[170:173], v[202:205], v[100:103]
	v_mfma_f32_16x16x32_bf16 v[88:91], v[162:165], v[210:213], v[88:91]
	v_mfma_f32_16x16x32_bf16 v[80:83], v[170:173], v[210:213], v[80:83]
	v_mfma_f32_16x16x32_bf16 v[72:75], v[162:165], v[218:221], v[72:75]
	v_mfma_f32_16x16x32_bf16 v[64:67], v[170:173], v[218:221], v[64:67]
	v_mfma_f32_16x16x32_bf16 v[124:127], v[166:169], v[182:185], v[124:127]
	v_mfma_f32_16x16x32_bf16 v[116:119], v[174:177], v[182:185], v[116:119]
	v_mfma_f32_16x16x32_bf16 v[108:111], v[166:169], v[206:209], v[108:111]
	v_mfma_f32_16x16x32_bf16 v[100:103], v[174:177], v[206:209], v[100:103]
	v_mfma_f32_16x16x32_bf16 v[88:91], v[166:169], v[214:217], v[88:91]
	v_mfma_f32_16x16x32_bf16 v[80:83], v[174:177], v[214:217], v[80:83]
	v_mfma_f32_16x16x32_bf16 v[72:75], v[166:169], v[222:225], v[72:75]
	v_mfma_f32_16x16x32_bf16 v[64:67], v[174:177], v[222:225], v[64:67]
	s_barrier
	s_add_i32 s30, s76, s56
	s_add_u32 s100, s36, 0x80
	s_addc_u32 s101, s37, 0
	s_mov_b32 m0, s30
	ds_read_b128 v[178:181], v149 offset:49152
	ds_read_b128 v[182:185], v149 offset:50176
	ds_read_b128 v[202:205], v149 offset:51200
	ds_read_b128 v[206:209], v149 offset:52224
	ds_read_b128 v[210:213], v149 offset:53248
	ds_read_b128 v[214:217], v149 offset:54272
	ds_read_b128 v[218:221], v149 offset:55296
	ds_read_b128 v[222:225], v149 offset:56320
	global_load_lds_dwordx4 v188, s[100:101]
	s_add_i32 m0, s30, 0x2000
	s_add_u32 s30, s36, 0x40080
	s_addc_u32 s31, s37, 0
	s_add_i32 s36, s77, s56
	global_load_lds_dwordx4 v132, s[100:101]
	s_mov_b32 m0, s36
	s_nop 0
	global_load_lds_dwordx4 v188, s[30:31]
	s_add_i32 m0, s36, 0x2000
	s_nop 0
	global_load_lds_dwordx4 v132, s[30:31]
	s_add_u32 s100, s38, 0x80
	s_addc_u32 s101, s39, 0
	s_mov_b32 m0, s90
	s_nop 0
	global_load_lds_dwordx4 v136, s[100:101]
	s_mov_b32 m0, s91
	s_nop 0
	global_load_lds_dwordx4 v134, s[100:101]
	s_waitcnt vmcnt(8)
	s_waitcnt lgkmcnt(0)
	s_barrier
	s_waitcnt lgkmcnt(0)
	v_mfma_f32_16x16x32_bf16 v[60:63], v[96:99], v[178:181], v[60:63]
	v_mfma_f32_16x16x32_bf16 v[52:55], v[154:157], v[178:181], v[52:55]
	v_mfma_f32_16x16x32_bf16 v[44:47], v[96:99], v[202:205], v[44:47]
	v_mfma_f32_16x16x32_bf16 v[36:39], v[154:157], v[202:205], v[36:39]
	v_mfma_f32_16x16x32_bf16 v[28:31], v[96:99], v[210:213], v[28:31]
	v_mfma_f32_16x16x32_bf16 v[20:23], v[154:157], v[210:213], v[20:23]
	v_mfma_f32_16x16x32_bf16 v[12:15], v[96:99], v[218:221], v[12:15]
	v_mfma_f32_16x16x32_bf16 v[4:7], v[154:157], v[218:221], v[4:7]
	v_mfma_f32_16x16x32_bf16 v[60:63], v[150:153], v[182:185], v[60:63]
	v_mfma_f32_16x16x32_bf16 v[52:55], v[158:161], v[182:185], v[52:55]
	v_mfma_f32_16x16x32_bf16 v[44:47], v[150:153], v[206:209], v[44:47]
	v_mfma_f32_16x16x32_bf16 v[36:39], v[158:161], v[206:209], v[36:39]
	v_mfma_f32_16x16x32_bf16 v[28:31], v[150:153], v[214:217], v[28:31]
	v_mfma_f32_16x16x32_bf16 v[20:23], v[158:161], v[214:217], v[20:23]
	v_mfma_f32_16x16x32_bf16 v[12:15], v[150:153], v[222:225], v[12:15]
	v_mfma_f32_16x16x32_bf16 v[4:7], v[158:161], v[222:225], v[4:7]
	v_mfma_f32_16x16x32_bf16 v[56:59], v[162:165], v[178:181], v[56:59]
	v_mfma_f32_16x16x32_bf16 v[48:51], v[170:173], v[178:181], v[48:51]
	v_mfma_f32_16x16x32_bf16 v[40:43], v[162:165], v[202:205], v[40:43]
	v_mfma_f32_16x16x32_bf16 v[32:35], v[170:173], v[202:205], v[32:35]
	v_mfma_f32_16x16x32_bf16 v[24:27], v[162:165], v[210:213], v[24:27]
	v_mfma_f32_16x16x32_bf16 v[16:19], v[170:173], v[210:213], v[16:19]
	v_mfma_f32_16x16x32_bf16 v[8:11], v[162:165], v[218:221], v[8:11]
	v_mfma_f32_16x16x32_bf16 v[0:3], v[170:173], v[218:221], v[0:3]
	v_mfma_f32_16x16x32_bf16 v[56:59], v[166:169], v[182:185], v[56:59]
	v_mfma_f32_16x16x32_bf16 v[48:51], v[174:177], v[182:185], v[48:51]
	v_mfma_f32_16x16x32_bf16 v[40:43], v[166:169], v[206:209], v[40:43]
	v_mfma_f32_16x16x32_bf16 v[32:35], v[174:177], v[206:209], v[32:35]
	v_mfma_f32_16x16x32_bf16 v[24:27], v[166:169], v[214:217], v[24:27]
	v_mfma_f32_16x16x32_bf16 v[16:19], v[174:177], v[214:217], v[16:19]
	v_mfma_f32_16x16x32_bf16 v[8:11], v[166:169], v[222:225], v[8:11]
	v_mfma_f32_16x16x32_bf16 v[0:3], v[174:177], v[222:225], v[0:3]
	s_barrier
	s_add_i32 s43, s43, 2
	s_cmp_gt_u32 s43, 13
	s_mov_b64 s[30:31], s[34:35]
	s_cbranch_scc0 .LBB0_528

.LBB0_531:
	s_setprio 0
	v_lshl_add_u32 v154, s54, 12, v145
	ds_read_b128 v[96:99], v154
	ds_read_b128 v[234:237], v154 offset:256
	s_waitcnt lgkmcnt(1)
	v_mov_b32_e32 v150, v97
	v_mov_b32_e32 v151, v98
	v_mov_b32_e32 v97, v99
	v_pk_add_f32 v[96:97], v[150:151], v[96:97]
	v_lshl_add_u32 v151, s24, 8, v139
	v_add_f32_e32 v96, v96, v97
	v_fmamk_f32 v96, v96, 0x3a800000, v229
	v_rsq_f32_e32 v150, v96
	ds_read_b128 v[96:99], v154 offset:512
	v_pk_mul_f32 v[128:129], v[128:129], v[150:151] op_sel_hi:[1,0]
	v_pk_mul_f32 v[124:125], v[124:125], v[150:151] op_sel_hi:[1,0]
	s_waitcnt lgkmcnt(1)
	v_mov_b32_e32 v152, v235
	v_mov_b32_e32 v153, v236
	v_mov_b32_e32 v235, v237
	v_pk_add_f32 v[234:235], v[152:153], v[234:235]
	v_pk_mul_f32 v[124:125], v[124:125], v[128:129]
	v_add_f32_e32 v234, v234, v235
	v_fmamk_f32 v234, v234, 0x3a800000, v229
	v_rsq_f32_e32 v148, v234
	ds_read_b128 v[234:237], v154 offset:768
	v_pk_mul_f32 v[128:129], v[128:129], s[68:69] op_sel_hi:[1,0]
	v_pk_mul_f32 v[126:127], v[126:127], v[150:151] op_sel_hi:[1,0]
	v_exp_f32_e32 v128, v128
	v_exp_f32_e32 v129, v129
	s_waitcnt lgkmcnt(1)
	v_mov_b32_e32 v152, v97
	v_mov_b32_e32 v153, v98
	v_mov_b32_e32 v97, v99
	v_pk_add_f32 v[96:97], v[152:153], v[96:97]
	v_pk_add_f32 v[128:129], v[128:129], 1.0 op_sel_hi:[1,0]
	v_add_f32_e32 v96, v96, v97
	v_fmamk_f32 v96, v96, 0x3a800000, v229
	v_rsq_f32_e32 v146, v96
	ds_read_b128 v[96:99], v154 offset:2048
	v_rcp_f32_e32 v128, v128
	v_rcp_f32_e32 v129, v129
	v_pk_mul_f32 v[120:121], v[120:121], v[150:151] op_sel_hi:[1,0]
	v_pk_mul_f32 v[116:117], v[116:117], v[150:151] op_sel_hi:[1,0]
	s_waitcnt lgkmcnt(1)
	v_mov_b32_e32 v152, v235
	v_mov_b32_e32 v153, v236
	v_mov_b32_e32 v235, v237
	v_pk_add_f32 v[234:235], v[152:153], v[234:235]
	v_pk_mul_f32 v[124:125], v[124:125], v[128:129]
	v_add_f32_e32 v234, v234, v235
	v_fmamk_f32 v234, v234, 0x3a800000, v229
	v_rsq_f32_e32 v144, v234
	ds_read_b128 v[234:237], v154 offset:2304
	v_pk_mul_f32 v[128:129], v[130:131], v[150:151] op_sel_hi:[1,0]
	v_pk_mul_f32 v[116:117], v[120:121], v[116:117]
	v_pk_mul_f32 v[126:127], v[128:129], v[126:127]
	v_pk_mul_f32 v[128:129], v[128:129], s[68:69] op_sel_hi:[1,0]
	s_waitcnt lgkmcnt(1)
	v_mov_b32_e32 v152, v97
	v_mov_b32_e32 v153, v98
	v_mov_b32_e32 v97, v99
	v_pk_add_f32 v[96:97], v[152:153], v[96:97]
	v_pk_mul_f32 v[120:121], v[120:121], s[68:69] op_sel_hi:[1,0]
	v_add_f32_e32 v96, v96, v97
	v_fmamk_f32 v96, v96, 0x3a800000, v229
	v_rsq_f32_e32 v142, v96
	ds_read_b128 v[96:99], v154 offset:2560
	v_exp_f32_e32 v128, v128
	v_exp_f32_e32 v129, v129
	v_exp_f32_e32 v120, v120
	v_exp_f32_e32 v121, v121
	s_waitcnt lgkmcnt(1)
	v_mov_b32_e32 v152, v235
	v_mov_b32_e32 v153, v236
	v_mov_b32_e32 v235, v237
	v_pk_add_f32 v[234:235], v[152:153], v[234:235]
	v_pk_mul_f32 v[112:113], v[112:113], v[148:149] op_sel_hi:[1,0]
	v_add_f32_e32 v234, v234, v235
	v_fmamk_f32 v234, v234, 0x3a800000, v229
	v_rsq_f32_e32 v140, v234
	ds_read_b128 v[234:237], v154 offset:2816
	v_pk_mul_f32 v[108:109], v[108:109], v[148:149] op_sel_hi:[1,0]
	v_pk_add_f32 v[128:129], v[128:129], 1.0 op_sel_hi:[1,0]
	v_pk_mul_f32 v[108:109], v[108:109], v[112:113]
	v_pk_mul_f32 v[112:113], v[112:113], s[68:69] op_sel_hi:[1,0]
	v_pk_add_f32 v[120:121], v[120:121], 1.0 op_sel_hi:[1,0]
	v_exp_f32_e32 v112, v112
	v_exp_f32_e32 v113, v113
	v_rcp_f32_e32 v128, v128
	v_rcp_f32_e32 v129, v129
	v_rcp_f32_e32 v120, v120
	v_rcp_f32_e32 v121, v121
	s_waitcnt lgkmcnt(1)
	v_mov_b32_e32 v152, v97
	v_mov_b32_e32 v153, v98
	v_mov_b32_e32 v97, v99
	v_pk_add_f32 v[96:97], v[152:153], v[96:97]
	v_pk_add_f32 v[112:113], v[112:113], 1.0 op_sel_hi:[1,0]
	v_add_f32_e32 v96, v96, v97
	v_fmamk_f32 v96, v96, 0x3a800000, v229
	v_pk_mul_f32 v[126:127], v[126:127], v[128:129]
	v_pk_mul_f32 v[116:117], v[116:117], v[120:121]
	v_rcp_f32_e32 v112, v112
	v_rcp_f32_e32 v113, v113
	v_rsq_f32_e32 v138, v96
	v_cvt_pk_bf16_f32 v124, v124, v125
	v_cvt_pk_bf16_f32 v125, v126, v127
	v_cvt_pk_bf16_f32 v126, v116, v117
	v_pk_mul_f32 v[116:117], v[122:123], v[150:151] op_sel_hi:[1,0]
	v_pk_mul_f32 v[118:119], v[118:119], v[150:151] op_sel_hi:[1,0]
	v_pk_mul_f32 v[108:109], v[108:109], v[112:113]
	v_pk_mul_f32 v[118:119], v[116:117], v[118:119]
	v_pk_mul_f32 v[116:117], v[116:117], s[68:69] op_sel_hi:[1,0]
	v_pk_mul_f32 v[112:113], v[114:115], v[148:149] op_sel_hi:[1,0]
	v_exp_f32_e32 v116, v116
	v_exp_f32_e32 v117, v117
	v_pk_mul_f32 v[110:111], v[110:111], v[148:149] op_sel_hi:[1,0]
	v_pk_mul_f32 v[104:105], v[104:105], v[148:149] op_sel_hi:[1,0]
	v_pk_mul_f32 v[100:101], v[100:101], v[148:149] op_sel_hi:[1,0]
	v_pk_mul_f32 v[110:111], v[112:113], v[110:111]
	v_pk_mul_f32 v[112:113], v[112:113], s[68:69] op_sel_hi:[1,0]
	v_pk_mul_f32 v[100:101], v[104:105], v[100:101]
	v_pk_mul_f32 v[104:105], v[104:105], s[68:69] op_sel_hi:[1,0]
	v_exp_f32_e32 v112, v112
	v_exp_f32_e32 v113, v113
	v_exp_f32_e32 v104, v104
	v_exp_f32_e32 v105, v105
	v_pk_add_f32 v[116:117], v[116:117], 1.0 op_sel_hi:[1,0]
	v_pk_mul_f32 v[92:93], v[92:93], v[146:147] op_sel_hi:[1,0]
	v_rcp_f32_e32 v116, v116
	v_rcp_f32_e32 v117, v117
	v_pk_mul_f32 v[88:89], v[88:89], v[146:147] op_sel_hi:[1,0]
	v_pk_add_f32 v[112:113], v[112:113], 1.0 op_sel_hi:[1,0]
	v_pk_mul_f32 v[88:89], v[88:89], v[92:93]
	v_pk_mul_f32 v[92:93], v[92:93], s[68:69] op_sel_hi:[1,0]
	v_pk_add_f32 v[104:105], v[104:105], 1.0 op_sel_hi:[1,0]
	v_exp_f32_e32 v92, v92
	v_exp_f32_e32 v93, v93
	v_rcp_f32_e32 v112, v112
	v_rcp_f32_e32 v113, v113
	v_rcp_f32_e32 v104, v104
	v_rcp_f32_e32 v105, v105
	v_lshl_or_b32 v152, s1, 7, v147
	v_pk_mul_f32 v[116:117], v[118:119], v[116:117]
	v_ashrrev_i32_e32 v153, 31, v152
	v_cvt_pk_bf16_f32 v127, v116, v117
	v_mov_b64_e32 v[116:117], s[8:9]
	v_mad_i64_i32 v[120:121], s[0:1], v151, s42, v[116:117]
	v_lshlrev_b64 v[118:119], 1, v[152:153]
	v_pk_add_f32 v[92:93], v[92:93], 1.0 op_sel_hi:[1,0]
	v_lshl_add_u64 v[120:121], v[120:121], 0, v[118:119]
	v_pk_mul_f32 v[110:111], v[110:111], v[112:113]
	v_pk_mul_f32 v[100:101], v[100:101], v[104:105]
	v_rcp_f32_e32 v92, v92
	v_rcp_f32_e32 v93, v93
	global_store_dwordx4 v[120:121], v[124:127], off
	v_cvt_pk_bf16_f32 v108, v108, v109
	v_cvt_pk_bf16_f32 v109, v110, v111
	v_cvt_pk_bf16_f32 v110, v100, v101
	v_pk_mul_f32 v[100:101], v[106:107], v[148:149] op_sel_hi:[1,0]
	v_pk_mul_f32 v[102:103], v[102:103], v[148:149] op_sel_hi:[1,0]
	v_pk_mul_f32 v[88:89], v[88:89], v[92:93]
	v_pk_mul_f32 v[102:103], v[100:101], v[102:103]
	v_pk_mul_f32 v[100:101], v[100:101], s[68:69] op_sel_hi:[1,0]
	v_pk_mul_f32 v[92:93], v[94:95], v[146:147] op_sel_hi:[1,0]
	v_exp_f32_e32 v100, v100
	v_exp_f32_e32 v101, v101
	v_pk_mul_f32 v[90:91], v[90:91], v[146:147] op_sel_hi:[1,0]
	v_pk_mul_f32 v[84:85], v[84:85], v[146:147] op_sel_hi:[1,0]
	v_pk_mul_f32 v[80:81], v[80:81], v[146:147] op_sel_hi:[1,0]
	v_pk_mul_f32 v[90:91], v[92:93], v[90:91]
	v_pk_mul_f32 v[92:93], v[92:93], s[68:69] op_sel_hi:[1,0]
	v_pk_mul_f32 v[80:81], v[84:85], v[80:81]
	v_pk_mul_f32 v[84:85], v[84:85], s[68:69] op_sel_hi:[1,0]
	v_exp_f32_e32 v92, v92
	v_exp_f32_e32 v93, v93
	v_exp_f32_e32 v84, v84
	v_exp_f32_e32 v85, v85
	v_pk_add_f32 v[100:101], v[100:101], 1.0 op_sel_hi:[1,0]
	v_pk_mul_f32 v[76:77], v[76:77], v[144:145] op_sel_hi:[1,0]
	v_rcp_f32_e32 v100, v100
	v_rcp_f32_e32 v101, v101
	v_pk_mul_f32 v[72:73], v[72:73], v[144:145] op_sel_hi:[1,0]
	v_pk_add_f32 v[92:93], v[92:93], 1.0 op_sel_hi:[1,0]
	v_pk_mul_f32 v[72:73], v[72:73], v[76:77]
	v_pk_mul_f32 v[76:77], v[76:77], s[68:69] op_sel_hi:[1,0]
	v_pk_add_f32 v[84:85], v[84:85], 1.0 op_sel_hi:[1,0]
	v_exp_f32_e32 v76, v76
	v_exp_f32_e32 v77, v77
	v_rcp_f32_e32 v92, v92
	v_rcp_f32_e32 v93, v93
	v_rcp_f32_e32 v84, v84
	v_rcp_f32_e32 v85, v85
	v_pk_mul_f32 v[100:101], v[102:103], v[100:101]
	v_pk_add_f32 v[76:77], v[76:77], 1.0 op_sel_hi:[1,0]
	v_cvt_pk_bf16_f32 v111, v100, v101
	v_or_b32_e32 v100, 16, v151
	v_mad_i64_i32 v[100:101], s[0:1], v100, s42, v[116:117]
	v_lshl_add_u64 v[100:101], v[100:101], 0, v[118:119]
	v_pk_mul_f32 v[90:91], v[90:91], v[92:93]
	v_pk_mul_f32 v[80:81], v[80:81], v[84:85]
	v_rcp_f32_e32 v76, v76
	v_rcp_f32_e32 v77, v77
	global_store_dwordx4 v[100:101], v[108:111], off
	v_cvt_pk_bf16_f32 v88, v88, v89
	v_cvt_pk_bf16_f32 v89, v90, v91
	v_cvt_pk_bf16_f32 v90, v80, v81
	v_pk_mul_f32 v[80:81], v[86:87], v[146:147] op_sel_hi:[1,0]
	v_pk_mul_f32 v[82:83], v[82:83], v[146:147] op_sel_hi:[1,0]
	v_pk_mul_f32 v[72:73], v[72:73], v[76:77]
	v_pk_mul_f32 v[82:83], v[80:81], v[82:83]
	v_pk_mul_f32 v[80:81], v[80:81], s[68:69] op_sel_hi:[1,0]
	v_pk_mul_f32 v[76:77], v[78:79], v[144:145] op_sel_hi:[1,0]
	v_exp_f32_e32 v80, v80
	v_exp_f32_e32 v81, v81
	v_pk_mul_f32 v[74:75], v[74:75], v[144:145] op_sel_hi:[1,0]
	v_pk_mul_f32 v[68:69], v[68:69], v[144:145] op_sel_hi:[1,0]
	v_pk_mul_f32 v[64:65], v[64:65], v[144:145] op_sel_hi:[1,0]
	v_pk_mul_f32 v[74:75], v[76:77], v[74:75]
	v_pk_mul_f32 v[76:77], v[76:77], s[68:69] op_sel_hi:[1,0]
	v_pk_mul_f32 v[64:65], v[68:69], v[64:65]
	v_pk_mul_f32 v[68:69], v[68:69], s[68:69] op_sel_hi:[1,0]
	v_exp_f32_e32 v76, v76
	v_exp_f32_e32 v77, v77
	v_exp_f32_e32 v68, v68
	v_exp_f32_e32 v69, v69
	v_pk_add_f32 v[80:81], v[80:81], 1.0 op_sel_hi:[1,0]
	v_pk_add_f32 v[76:77], v[76:77], 1.0 op_sel_hi:[1,0]
	v_rcp_f32_e32 v80, v80
	v_rcp_f32_e32 v81, v81
	v_pk_add_f32 v[68:69], v[68:69], 1.0 op_sel_hi:[1,0]
	v_rcp_f32_e32 v76, v76
	v_rcp_f32_e32 v77, v77
	v_rcp_f32_e32 v68, v68
	v_rcp_f32_e32 v69, v69
	v_pk_mul_f32 v[80:81], v[82:83], v[80:81]
	v_pk_mul_f32 v[74:75], v[74:75], v[76:77]
	v_cvt_pk_bf16_f32 v91, v80, v81
	v_or_b32_e32 v80, 32, v151
	v_mad_i64_i32 v[80:81], s[0:1], v80, s42, v[116:117]
	v_lshl_add_u64 v[80:81], v[80:81], 0, v[118:119]
	v_pk_mul_f32 v[64:65], v[64:65], v[68:69]
	global_store_dwordx4 v[80:81], v[88:91], off
	v_cvt_pk_bf16_f32 v72, v72, v73
	v_cvt_pk_bf16_f32 v73, v74, v75
	v_cvt_pk_bf16_f32 v74, v64, v65
	v_pk_mul_f32 v[64:65], v[70:71], v[144:145] op_sel_hi:[1,0]
	v_pk_mul_f32 v[66:67], v[66:67], v[144:145] op_sel_hi:[1,0]
	s_nop 0
	v_pk_mul_f32 v[66:67], v[64:65], v[66:67]
	v_pk_mul_f32 v[64:65], v[64:65], s[68:69] op_sel_hi:[1,0]
	s_nop 0
	v_exp_f32_e32 v64, v64
	v_exp_f32_e32 v65, v65
	s_nop 0
	v_pk_add_f32 v[64:65], v[64:65], 1.0 op_sel_hi:[1,0]
	s_nop 0
	v_rcp_f32_e32 v64, v64
	v_rcp_f32_e32 v65, v65
	s_nop 0
	v_pk_mul_f32 v[64:65], v[66:67], v[64:65]
	s_nop 0
	v_cvt_pk_bf16_f32 v75, v64, v65
	v_or_b32_e32 v64, 48, v151
	v_mad_i64_i32 v[64:65], s[0:1], v64, s42, v[116:117]
	v_lshl_add_u64 v[64:65], v[64:65], 0, v[118:119]
	global_store_dwordx4 v[64:65], v[72:75], off
	v_add_u32_e32 v64, 0x80, v151
	v_pk_mul_f32 v[60:61], v[60:61], v[142:143] op_sel_hi:[1,0]
	v_pk_mul_f32 v[56:57], v[56:57], v[142:143] op_sel_hi:[1,0]
	v_pk_mul_f32 v[58:59], v[58:59], v[142:143] op_sel_hi:[1,0]
	v_pk_mul_f32 v[56:57], v[60:61], v[56:57]
	v_pk_mul_f32 v[60:61], v[60:61], s[68:69] op_sel_hi:[1,0]
	v_pk_mul_f32 v[52:53], v[52:53], v[142:143] op_sel_hi:[1,0]
	v_exp_f32_e32 v60, v60
	v_exp_f32_e32 v61, v61
	v_pk_mul_f32 v[48:49], v[48:49], v[142:143] op_sel_hi:[1,0]
	v_pk_mul_f32 v[44:45], v[44:45], v[140:141] op_sel_hi:[1,0]
	v_pk_mul_f32 v[48:49], v[52:53], v[48:49]
	v_pk_add_f32 v[60:61], v[60:61], 1.0 op_sel_hi:[1,0]
	v_pk_mul_f32 v[52:53], v[52:53], s[68:69] op_sel_hi:[1,0]
	v_rcp_f32_e32 v60, v60
	v_rcp_f32_e32 v61, v61
	v_exp_f32_e32 v52, v52
	v_exp_f32_e32 v53, v53
	v_pk_mul_f32 v[40:41], v[40:41], v[140:141] op_sel_hi:[1,0]
	v_pk_mul_f32 v[56:57], v[56:57], v[60:61]
	v_pk_mul_f32 v[60:61], v[62:63], v[142:143] op_sel_hi:[1,0]
	v_pk_mul_f32 v[40:41], v[40:41], v[44:45]
	v_pk_mul_f32 v[58:59], v[60:61], v[58:59]
	v_pk_mul_f32 v[60:61], v[60:61], s[68:69] op_sel_hi:[1,0]
	v_pk_mul_f32 v[44:45], v[44:45], s[68:69] op_sel_hi:[1,0]
	v_exp_f32_e32 v60, v60
	v_exp_f32_e32 v61, v61
	v_exp_f32_e32 v44, v44
	v_exp_f32_e32 v45, v45
	v_pk_add_f32 v[52:53], v[52:53], 1.0 op_sel_hi:[1,0]
	v_pk_add_f32 v[60:61], v[60:61], 1.0 op_sel_hi:[1,0]
	v_rcp_f32_e32 v52, v52
	v_rcp_f32_e32 v60, v60
	v_rcp_f32_e32 v61, v61
	v_rcp_f32_e32 v53, v53
	v_pk_add_f32 v[44:45], v[44:45], 1.0 op_sel_hi:[1,0]
	v_cvt_pk_bf16_f32 v56, v56, v57
	v_pk_mul_f32 v[58:59], v[58:59], v[60:61]
	v_rcp_f32_e32 v44, v44
	v_rcp_f32_e32 v45, v45
	v_pk_mul_f32 v[48:49], v[48:49], v[52:53]
	v_cvt_pk_bf16_f32 v57, v58, v59
	v_pk_mul_f32 v[50:51], v[50:51], v[142:143] op_sel_hi:[1,0]
	v_cvt_pk_bf16_f32 v58, v48, v49
	v_pk_mul_f32 v[48:49], v[54:55], v[142:143] op_sel_hi:[1,0]
	v_pk_mul_f32 v[40:41], v[40:41], v[44:45]
	v_pk_mul_f32 v[50:51], v[48:49], v[50:51]
	v_pk_mul_f32 v[48:49], v[48:49], s[68:69] op_sel_hi:[1,0]
	v_pk_mul_f32 v[44:45], v[46:47], v[140:141] op_sel_hi:[1,0]
	v_exp_f32_e32 v48, v48
	v_exp_f32_e32 v49, v49
	v_pk_mul_f32 v[42:43], v[42:43], v[140:141] op_sel_hi:[1,0]
	v_pk_mul_f32 v[36:37], v[36:37], v[140:141] op_sel_hi:[1,0]
	v_pk_mul_f32 v[32:33], v[32:33], v[140:141] op_sel_hi:[1,0]
	v_pk_mul_f32 v[42:43], v[44:45], v[42:43]
	v_pk_mul_f32 v[44:45], v[44:45], s[68:69] op_sel_hi:[1,0]
	v_pk_mul_f32 v[32:33], v[36:37], v[32:33]
	v_pk_mul_f32 v[36:37], v[36:37], s[68:69] op_sel_hi:[1,0]
	v_exp_f32_e32 v44, v44
	v_exp_f32_e32 v45, v45
	v_exp_f32_e32 v36, v36
	v_exp_f32_e32 v37, v37
	v_pk_add_f32 v[48:49], v[48:49], 1.0 op_sel_hi:[1,0]
	v_pk_mul_f32 v[28:29], v[28:29], v[138:139] op_sel_hi:[1,0]
	v_pk_mul_f32 v[24:25], v[24:25], v[138:139] op_sel_hi:[1,0]
	v_rcp_f32_e32 v48, v48
	v_rcp_f32_e32 v49, v49
	v_pk_mul_f32 v[24:25], v[24:25], v[28:29]
	v_pk_mul_f32 v[28:29], v[28:29], s[68:69] op_sel_hi:[1,0]
	v_pk_add_f32 v[44:45], v[44:45], 1.0 op_sel_hi:[1,0]
	v_pk_add_f32 v[36:37], v[36:37], 1.0 op_sel_hi:[1,0]
	v_exp_f32_e32 v28, v28
	v_exp_f32_e32 v29, v29
	v_rcp_f32_e32 v44, v44
	v_rcp_f32_e32 v45, v45
	v_rcp_f32_e32 v36, v36
	v_rcp_f32_e32 v37, v37
	v_pk_mul_f32 v[48:49], v[50:51], v[48:49]
	v_pk_add_f32 v[28:29], v[28:29], 1.0 op_sel_hi:[1,0]
	v_cvt_pk_bf16_f32 v59, v48, v49
	v_mad_i64_i32 v[48:49], s[0:1], v64, s42, v[116:117]
	v_lshl_add_u64 v[48:49], v[48:49], 0, v[118:119]
	v_pk_mul_f32 v[42:43], v[42:43], v[44:45]
	v_pk_mul_f32 v[32:33], v[32:33], v[36:37]
	v_rcp_f32_e32 v28, v28
	v_rcp_f32_e32 v29, v29
	global_store_dwordx4 v[48:49], v[56:59], off
	v_cvt_pk_bf16_f32 v40, v40, v41
	v_cvt_pk_bf16_f32 v41, v42, v43
	v_cvt_pk_bf16_f32 v42, v32, v33
	v_pk_mul_f32 v[32:33], v[38:39], v[140:141] op_sel_hi:[1,0]
	v_pk_mul_f32 v[34:35], v[34:35], v[140:141] op_sel_hi:[1,0]
	v_pk_mul_f32 v[24:25], v[24:25], v[28:29]
	v_pk_mul_f32 v[34:35], v[32:33], v[34:35]
	v_pk_mul_f32 v[32:33], v[32:33], s[68:69] op_sel_hi:[1,0]
	v_pk_mul_f32 v[28:29], v[30:31], v[138:139] op_sel_hi:[1,0]
	v_exp_f32_e32 v32, v32
	v_exp_f32_e32 v33, v33
	v_pk_mul_f32 v[26:27], v[26:27], v[138:139] op_sel_hi:[1,0]
	v_pk_mul_f32 v[20:21], v[20:21], v[138:139] op_sel_hi:[1,0]
	v_pk_mul_f32 v[16:17], v[16:17], v[138:139] op_sel_hi:[1,0]
	v_pk_mul_f32 v[26:27], v[28:29], v[26:27]
	v_pk_mul_f32 v[28:29], v[28:29], s[68:69] op_sel_hi:[1,0]
	v_pk_mul_f32 v[16:17], v[20:21], v[16:17]
	v_pk_mul_f32 v[20:21], v[20:21], s[68:69] op_sel_hi:[1,0]
	v_exp_f32_e32 v28, v28
	v_exp_f32_e32 v29, v29
	v_exp_f32_e32 v20, v20
	v_exp_f32_e32 v21, v21
	v_pk_add_f32 v[32:33], v[32:33], 1.0 op_sel_hi:[1,0]
	v_pk_add_f32 v[28:29], v[28:29], 1.0 op_sel_hi:[1,0]
	v_rcp_f32_e32 v32, v32
	v_rcp_f32_e32 v33, v33
	v_pk_add_f32 v[20:21], v[20:21], 1.0 op_sel_hi:[1,0]
	v_rcp_f32_e32 v28, v28
	v_rcp_f32_e32 v29, v29
	v_rcp_f32_e32 v20, v20
	v_rcp_f32_e32 v21, v21
	v_pk_mul_f32 v[32:33], v[34:35], v[32:33]
	v_pk_mul_f32 v[26:27], v[26:27], v[28:29]
	v_cvt_pk_bf16_f32 v43, v32, v33
	v_add_u32_e32 v32, 0x90, v151
	v_mad_i64_i32 v[32:33], s[0:1], v32, s42, v[116:117]
	v_lshl_add_u64 v[32:33], v[32:33], 0, v[118:119]
	v_pk_mul_f32 v[16:17], v[16:17], v[20:21]
	global_store_dwordx4 v[32:33], v[40:43], off
	v_cvt_pk_bf16_f32 v24, v24, v25
	v_cvt_pk_bf16_f32 v25, v26, v27
	v_cvt_pk_bf16_f32 v26, v16, v17
	v_pk_mul_f32 v[16:17], v[22:23], v[138:139] op_sel_hi:[1,0]
	v_pk_mul_f32 v[18:19], v[18:19], v[138:139] op_sel_hi:[1,0]
	s_mov_b64 s[24:25], -1
	v_pk_mul_f32 v[18:19], v[16:17], v[18:19]
	v_pk_mul_f32 v[16:17], v[16:17], s[68:69] op_sel_hi:[1,0]
	s_andn2_b64 vcc, exec, s[4:5]
	v_exp_f32_e32 v16, v16
	v_exp_f32_e32 v17, v17
	s_nop 0
	v_pk_add_f32 v[16:17], v[16:17], 1.0 op_sel_hi:[1,0]
	s_nop 0
	v_rcp_f32_e32 v16, v16
	v_rcp_f32_e32 v17, v17
	s_nop 0
	v_pk_mul_f32 v[16:17], v[18:19], v[16:17]
	s_nop 0
	v_cvt_pk_bf16_f32 v27, v16, v17
	v_add_u32_e32 v16, 0xa0, v151
	v_mad_i64_i32 v[16:17], s[0:1], v16, s42, v[116:117]
	v_lshl_add_u64 v[16:17], v[16:17], 0, v[118:119]
	global_store_dwordx4 v[16:17], v[24:27], off
	s_waitcnt lgkmcnt(0)
	v_mov_b32_e32 v16, v235
	v_mov_b32_e32 v17, v236
	v_mov_b32_e32 v235, v237
	v_pk_add_f32 v[16:17], v[16:17], v[234:235]
	s_nop 0
	v_add_f32_e32 v16, v16, v17
	v_fmamk_f32 v16, v16, 0x3a800000, v229
	v_rsq_f32_e32 v16, v16
	s_nop 0
	v_pk_mul_f32 v[12:13], v[12:13], v[16:17] op_sel_hi:[1,0]
	v_pk_mul_f32 v[8:9], v[8:9], v[16:17] op_sel_hi:[1,0]
	v_pk_mul_f32 v[10:11], v[10:11], v[16:17] op_sel_hi:[1,0]
	v_pk_mul_f32 v[8:9], v[8:9], v[12:13]
	v_pk_mul_f32 v[12:13], v[12:13], s[68:69] op_sel_hi:[1,0]
	v_pk_mul_f32 v[4:5], v[4:5], v[16:17] op_sel_hi:[1,0]
	v_exp_f32_e32 v12, v12
	v_exp_f32_e32 v13, v13
	v_pk_mul_f32 v[0:1], v[0:1], v[16:17] op_sel_hi:[1,0]
	v_pk_mul_f32 v[2:3], v[2:3], v[16:17] op_sel_hi:[1,0]
	v_pk_mul_f32 v[0:1], v[4:5], v[0:1]
	v_pk_add_f32 v[12:13], v[12:13], 1.0 op_sel_hi:[1,0]
	v_pk_mul_f32 v[4:5], v[4:5], s[68:69] op_sel_hi:[1,0]
	v_rcp_f32_e32 v12, v12
	v_rcp_f32_e32 v13, v13
	v_exp_f32_e32 v4, v4
	v_exp_f32_e32 v5, v5
	v_pk_mul_f32 v[8:9], v[8:9], v[12:13]
	v_pk_mul_f32 v[12:13], v[14:15], v[16:17] op_sel_hi:[1,0]
	v_pk_add_f32 v[4:5], v[4:5], 1.0 op_sel_hi:[1,0]
	v_pk_mul_f32 v[10:11], v[12:13], v[10:11]
	v_pk_mul_f32 v[12:13], v[12:13], s[68:69] op_sel_hi:[1,0]
	v_rcp_f32_e32 v4, v4
	v_exp_f32_e32 v12, v12
	v_exp_f32_e32 v13, v13
	v_rcp_f32_e32 v5, v5
	v_cvt_pk_bf16_f32 v8, v8, v9
	v_pk_add_f32 v[12:13], v[12:13], 1.0 op_sel_hi:[1,0]
	s_nop 0
	v_rcp_f32_e32 v12, v12
	v_rcp_f32_e32 v13, v13
	v_pk_mul_f32 v[0:1], v[0:1], v[4:5]
	v_pk_mul_f32 v[10:11], v[10:11], v[12:13]
	s_nop 0
	v_cvt_pk_bf16_f32 v9, v10, v11
	v_cvt_pk_bf16_f32 v10, v0, v1
	v_pk_mul_f32 v[0:1], v[6:7], v[16:17] op_sel_hi:[1,0]
	s_nop 0
	v_pk_mul_f32 v[2:3], v[0:1], v[2:3]
	v_pk_mul_f32 v[0:1], v[0:1], s[68:69] op_sel_hi:[1,0]
	s_nop 0
	v_exp_f32_e32 v0, v0
	v_exp_f32_e32 v1, v1
	s_nop 0
	v_pk_add_f32 v[0:1], v[0:1], 1.0 op_sel_hi:[1,0]
	s_nop 0
	v_rcp_f32_e32 v0, v0
	v_rcp_f32_e32 v1, v1
	s_nop 0
	v_pk_mul_f32 v[0:1], v[2:3], v[0:1]
	s_nop 0
	v_cvt_pk_bf16_f32 v11, v0, v1
	v_add_u32_e32 v0, 0xb0, v151
	v_mad_i64_i32 v[0:1], s[0:1], v0, s42, v[116:117]
	v_lshl_add_u64 v[0:1], v[0:1], 0, v[118:119]
	global_store_dwordx4 v[0:1], v[8:11], off
	s_cbranch_vccnz .LBB0_522
	s_andn2_b64 vcc, exec, s[6:7]
	s_cbranch_vccnz .LBB0_521
	s_barrier
	s_branch .LBB0_521
